# nt (streaming) cache policy on P3 epilogue stores and on the f32 residual X stores of P2/P6/P8
# speedup vs baseline: 1.0099x; 1.0099x over previous
; __device__ __forceinline__ unsigned cvtpk(float lo, float hi) { f32x2_t v = {lo, hi}; bf16x2_t b = __builtin_convertvector(v, bf16x2_t); return __builtin_bit_cast(unsigned, b); }
;     __device__ __forceinline__ void operator()(const pg8::f32x4 (&acc)[2][2][4][2], const pg8::Unit& u, int wr, int wc, int fr, int fq) const {
;         const int row0 = u.pm * 256 + wr * 64 + fr, colb = u.pn * 256 + wc * 32 + 8 * fq;
; #pragma unroll
;         for (int ai = 0; ai < 2; ++ai) {
;             pg8::f32x4 rv[4][2][2];
; #pragma unroll
;             for (int m = 0; m < 4; ++m)
; #pragma unroll
;                 for (int bj = 0; bj < 2; ++bj) { const size_t off = (size_t)(row0 + ai * 128 + m * 16) * DM + colb + bj * 128;
;                     rv[m][bj][0] = *(const pg8::f32x4*)(R + off); rv[m][bj][1] = *(const pg8::f32x4*)(R + off + 4); }
; #pragma unroll
;             for (int m = 0; m < 4; ++m) {
;                 const int row = row0 + ai * 128 + m * 16;
;                 float sq = 0.f;
; #pragma unroll
;                 for (int bj = 0; bj < 2; ++bj) {
;                     const size_t off = (size_t)row * DM + colb + bj * 128;
;                     const pg8::f32x4 v0 = rv[m][bj][0] + acc[ai][bj][m][0] * alpha, v1 = rv[m][bj][1] + acc[ai][bj][m][1] * alpha;
;                     *(pg8::f32x4*)(X + off) = v0; *(pg8::f32x4*)(X + off + 4) = v1;
;                     u32x4 w; w[0] = cvtpk(v0[0], v0[1]); w[1] = cvtpk(v0[2], v0[3]); w[2] = cvtpk(v1[0], v1[1]); w[3] = cvtpk(v1[2], v1[3]);
;                     *(u32x4*)(XB + off) = w;
;                     sq += (v0[0] * v0[0] + v0[1] * v0[1]) + (v0[2] * v0[2] + v0[3] * v0[3]) + (v1[0] * v1[0] + v1[1] * v1[1]) + (v1[2] * v1[2] + v1[3] * v1[3]);
;                 }
;                 sq += __shfl_xor(sq, 16); sq += __shfl_xor(sq, 32);
;                 if (fq == 0) atomicAdd(ssout + row, sq);
;             }
.LBB0_288:
	v_lshl_add_u32 v194, s44, 8, v205
	v_lshl_or_b32 v192, s45, 8, v207
	v_ashrrev_i32_e32 v193, 31, v192
	v_ashrrev_i32_e32 v195, 31, v194
	v_lshl_add_u64 v[196:197], v[192:193], 2, s[36:37]
	v_lshlrev_b64 v[128:129], 13, v[194:195]
	v_lshl_add_u64 v[128:129], v[196:197], 0, v[128:129]
	global_load_dwordx4 v[214:217], v[128:129], off
	global_load_dwordx4 v[222:225], v[128:129], off offset:16
	global_load_dwordx4 v[226:229], v[128:129], off offset:512
	global_load_dwordx4 v[230:233], v[128:129], off offset:528
	v_or_b32_e32 v202, 16, v194
	v_or_b32_e32 v200, 32, v194
	v_or_b32_e32 v198, 48, v194
	v_ashrrev_i32_e32 v203, 31, v202
	v_ashrrev_i32_e32 v201, 31, v200
	v_ashrrev_i32_e32 v199, 31, v198
	v_lshlrev_b64 v[128:129], 13, v[202:203]
	v_lshlrev_b64 v[130:131], 13, v[200:201]
	v_lshlrev_b64 v[132:133], 13, v[198:199]
	v_lshl_add_u64 v[128:129], v[196:197], 0, v[128:129]
	v_lshl_add_u64 v[130:131], v[196:197], 0, v[130:131]
	v_lshl_add_u64 v[132:133], v[196:197], 0, v[132:133]
	global_load_dwordx4 v[168:171], v[128:129], off offset:16
	global_load_dwordx4 v[172:175], v[128:129], off
	global_load_dwordx4 v[160:163], v[128:129], off offset:528
	global_load_dwordx4 v[164:167], v[128:129], off offset:512
	global_load_dwordx4 v[152:155], v[130:131], off offset:16
	global_load_dwordx4 v[156:159], v[130:131], off
	global_load_dwordx4 v[144:147], v[130:131], off offset:528
	global_load_dwordx4 v[148:151], v[130:131], off offset:512
	global_load_dwordx4 v[136:139], v[132:133], off offset:16
	global_load_dwordx4 v[140:143], v[132:133], off
	s_nop 0
	global_load_dwordx4 v[128:131], v[132:133], off offset:528
	s_nop 0
	global_load_dwordx4 v[132:135], v[132:133], off offset:512
	v_and_b32_e32 v213, 64, v211
	v_xor_b32_e32 v212, 16, v211
	v_add_u32_e32 v213, 64, v213
	v_xor_b32_e32 v218, 32, v211
	v_cmp_lt_i32_e32 vcc, v212, v213
	s_waitcnt vmcnt(0)
	v_pk_fma_f32 v[126:127], v[126:127], 0.5, v[216:217] op_sel_hi:[1,0,1]
	v_cndmask_b32_e32 v212, v211, v212, vcc
	v_cmp_lt_i32_e32 vcc, v218, v213
	v_pk_fma_f32 v[124:125], v[124:125], 0.5, v[214:215] op_sel_hi:[1,0,1]
	v_pk_fma_f32 v[118:119], v[118:119], 0.5, v[228:229] op_sel_hi:[1,0,1]
	v_cndmask_b32_e32 v221, v211, v218, vcc
	v_lshlrev_b64 v[218:219], 11, v[194:195]
	v_lshl_add_u64 v[218:219], v[218:219], 0, v[192:193]
	v_lshl_add_u64 v[234:235], v[218:219], 2, s[62:63]
	v_pk_fma_f32 v[116:117], v[116:117], 0.5, v[226:227] op_sel_hi:[1,0,1]
	v_lshlrev_b32_e32 v213, 2, v212
	v_lshlrev_b32_e32 v212, 2, v221
	v_pk_fma_f32 v[122:123], v[122:123], 0.5, v[224:225] op_sel_hi:[1,0,1]
	v_pk_fma_f32 v[120:121], v[120:121], 0.5, v[222:223] op_sel_hi:[1,0,1]
	v_pk_fma_f32 v[112:113], v[112:113], 0.5, v[230:231] op_sel_hi:[1,0,1]
	global_store_dwordx4 v[234:235], v[124:127], off nt
	global_store_dwordx4 v[234:235], v[120:123], off offset:16 nt
	v_cvt_pk_bf16_f32 v214, v124, v125
	v_cvt_pk_bf16_f32 v215, v126, v127
	v_mul_f32_e32 v125, v125, v125
	v_mul_f32_e32 v127, v127, v127
	v_mul_f32_e32 v221, v117, v117
	v_mul_f32_e32 v222, v119, v119
	v_pk_fma_f32 v[114:115], v[114:115], 0.5, v[232:233] op_sel_hi:[1,0,1]
	v_cvt_pk_bf16_f32 v216, v120, v121
	v_cvt_pk_bf16_f32 v217, v122, v123
	v_mul_f32_e32 v121, v121, v121
	v_mul_f32_e32 v123, v123, v123
	v_mul_f32_e32 v223, v113, v113
	v_fmac_f32_e32 v125, v124, v124
	v_fmac_f32_e32 v127, v126, v126
	v_fmac_f32_e32 v221, v116, v116
	v_fmac_f32_e32 v222, v118, v118
	v_mul_f32_e32 v224, v115, v115
	v_fmac_f32_e32 v121, v120, v120
	v_fmac_f32_e32 v123, v122, v122
	v_fmac_f32_e32 v223, v112, v112
	v_add_f32_e32 v120, v125, v127
	v_add_f32_e32 v122, v221, v222
	v_fmac_f32_e32 v224, v114, v114
	v_add_f32_e32 v120, v121, v120
	v_add_f32_e32 v121, v223, v122
	v_add_f32_e32 v120, v123, v120
	v_add_f32_e32 v121, v224, v121
	v_add_f32_e32 v120, v120, v121
	ds_bpermute_b32 v121, v213, v120
	v_lshlrev_b64 v[218:219], 1, v[218:219]
	v_lshl_add_u64 v[236:237], s[80:81], 0, v[218:219]
	global_store_dwordx4 v[236:237], v[214:217], off
	global_store_dwordx4 v[234:235], v[116:119], off offset:512 nt
	global_store_dwordx4 v[234:235], v[112:115], off offset:528 nt
	v_or_b32_e32 v218, 0x100, v218
	v_cvt_pk_bf16_f32 v116, v116, v117
	v_cvt_pk_bf16_f32 v117, v118, v119
	v_cvt_pk_bf16_f32 v118, v112, v113
	s_waitcnt lgkmcnt(0)
	v_add_f32_e32 v112, v120, v121
	ds_bpermute_b32 v113, v212, v112
	v_cvt_pk_bf16_f32 v119, v114, v115
	v_lshl_add_u64 v[114:115], s[80:81], 0, v[218:219]
	global_store_dwordx4 v[114:115], v[116:119], off
	s_and_saveexec_b64 s[20:21], s[2:3]
	s_cbranch_execz .LBB0_290
	v_lshl_add_u64 v[114:115], v[194:195], 2, s[12:13]
	s_waitcnt lgkmcnt(0)
	v_add_f32_e32 v112, v112, v113
	global_atomic_add_f32 v[114:115], v112, off
; __device__ __forceinline__ unsigned cvtpk(float lo, float hi) { f32x2_t v = {lo, hi}; bf16x2_t b = __builtin_convertvector(v, bf16x2_t); return __builtin_bit_cast(unsigned, b); }
;     __device__ __forceinline__ void operator()(const pg8::f32x4 (&acc)[2][2][4][2], const pg8::Unit& u, int wr, int wc, int fr, int fq) const {
;     ...
;             for (int m = 0; m < 4; ++m) {
;                 const int row = row0 + ai * 128 + m * 16;
;                 float sq = 0.f;
; #pragma unroll
;                 for (int bj = 0; bj < 2; ++bj) {
;                     const size_t off = (size_t)row * DM + colb + bj * 128;
;                     const pg8::f32x4 v0 = rv[m][bj][0] + acc[ai][bj][m][0] * alpha, v1 = rv[m][bj][1] + acc[ai][bj][m][1] * alpha;
;                     *(pg8::f32x4*)(X + off) = v0; *(pg8::f32x4*)(X + off + 4) = v1;
;                     u32x4 w; w[0] = cvtpk(v0[0], v0[1]); w[1] = cvtpk(v0[2], v0[3]); w[2] = cvtpk(v1[0], v1[1]); w[3] = cvtpk(v1[2], v1[3]);
;                     *(u32x4*)(XB + off) = w;
;                     sq += (v0[0] * v0[0] + v0[1] * v0[1]) + (v0[2] * v0[2] + v0[3] * v0[3]) + (v1[0] * v1[0] + v1[1] * v1[1]) + (v1[2] * v1[2] + v1[3] * v1[3]);
;                 }
;                 sq += __shfl_xor(sq, 16); sq += __shfl_xor(sq, 32);
;                 if (fq == 0) atomicAdd(ssout + row, sq);
;             }
.LBB0_290:
	s_or_b64 exec, exec, s[20:21]
	s_waitcnt lgkmcnt(0)
	v_lshlrev_b64 v[112:113], 11, v[202:203]
	v_lshl_add_u64 v[116:117], v[112:113], 0, v[192:193]
	v_pk_fma_f32 v[110:111], v[110:111], 0.5, v[174:175] op_sel_hi:[1,0,1]
	v_pk_fma_f32 v[108:109], v[108:109], 0.5, v[172:173] op_sel_hi:[1,0,1]
	v_lshl_add_u64 v[118:119], v[116:117], 2, s[62:63]
	v_pk_fma_f32 v[106:107], v[106:107], 0.5, v[170:171] op_sel_hi:[1,0,1]
	v_pk_fma_f32 v[104:105], v[104:105], 0.5, v[168:169] op_sel_hi:[1,0,1]
	global_store_dwordx4 v[118:119], v[108:111], off nt
	global_store_dwordx4 v[118:119], v[104:107], off offset:16 nt
	v_cvt_pk_bf16_f32 v112, v108, v109
	v_mul_f32_e32 v109, v109, v109
	v_fmac_f32_e32 v109, v108, v108
	v_mul_f32_e32 v108, v111, v111
	v_cvt_pk_bf16_f32 v114, v104, v105
	v_fmac_f32_e32 v108, v110, v110
	v_mul_f32_e32 v105, v105, v105
	v_add_f32_e32 v108, v109, v108
	v_fmac_f32_e32 v105, v104, v104
	v_add_f32_e32 v104, v105, v108
	v_mul_f32_e32 v105, v107, v107
	v_fmac_f32_e32 v105, v106, v106
	v_pk_fma_f32 v[102:103], v[102:103], 0.5, v[166:167] op_sel_hi:[1,0,1]
	v_pk_fma_f32 v[100:101], v[100:101], 0.5, v[164:165] op_sel_hi:[1,0,1]
	v_cvt_pk_bf16_f32 v115, v106, v107
	v_add_f32_e32 v104, v105, v104
	v_mul_f32_e32 v105, v101, v101
	v_mul_f32_e32 v106, v103, v103
	v_pk_fma_f32 v[96:97], v[96:97], 0.5, v[160:161] op_sel_hi:[1,0,1]
	v_fmac_f32_e32 v105, v100, v100
	v_fmac_f32_e32 v106, v102, v102
	v_add_f32_e32 v105, v105, v106
	v_mul_f32_e32 v106, v97, v97
	v_pk_fma_f32 v[98:99], v[98:99], 0.5, v[162:163] op_sel_hi:[1,0,1]
	v_fmac_f32_e32 v106, v96, v96
	v_add_f32_e32 v105, v106, v105
	v_mul_f32_e32 v106, v99, v99
	v_fmac_f32_e32 v106, v98, v98
	v_add_f32_e32 v105, v106, v105
	v_add_f32_e32 v104, v104, v105
	ds_bpermute_b32 v105, v213, v104
	v_lshlrev_b64 v[116:117], 1, v[116:117]
	v_cvt_pk_bf16_f32 v113, v110, v111
	v_lshl_add_u64 v[120:121], s[80:81], 0, v[116:117]
	global_store_dwordx4 v[120:121], v[112:115], off
	global_store_dwordx4 v[118:119], v[100:103], off offset:512 nt
	global_store_dwordx4 v[118:119], v[96:99], off offset:528 nt
	v_or_b32_e32 v116, 0x100, v116
	v_cvt_pk_bf16_f32 v100, v100, v101
	v_cvt_pk_bf16_f32 v101, v102, v103
	v_cvt_pk_bf16_f32 v102, v96, v97
	s_waitcnt lgkmcnt(0)
	v_add_f32_e32 v96, v104, v105
	ds_bpermute_b32 v97, v212, v96
	v_cvt_pk_bf16_f32 v103, v98, v99
	v_lshl_add_u64 v[98:99], s[80:81], 0, v[116:117]
	global_store_dwordx4 v[98:99], v[100:103], off
	s_and_saveexec_b64 s[20:21], s[2:3]
	s_cbranch_execz .LBB0_292
	v_lshl_add_u64 v[98:99], v[202:203], 2, s[12:13]
	s_waitcnt lgkmcnt(0)
	v_add_f32_e32 v96, v96, v97
	global_atomic_add_f32 v[98:99], v96, off
.LBB0_292:
	s_or_b64 exec, exec, s[20:21]
	s_waitcnt lgkmcnt(0)
	v_lshlrev_b64 v[96:97], 11, v[200:201]
	v_lshl_add_u64 v[100:101], v[96:97], 0, v[192:193]
	v_pk_fma_f32 v[94:95], v[94:95], 0.5, v[158:159] op_sel_hi:[1,0,1]
	v_pk_fma_f32 v[92:93], v[92:93], 0.5, v[156:157] op_sel_hi:[1,0,1]
	v_lshl_add_u64 v[102:103], v[100:101], 2, s[62:63]
	v_pk_fma_f32 v[90:91], v[90:91], 0.5, v[154:155] op_sel_hi:[1,0,1]
	v_pk_fma_f32 v[88:89], v[88:89], 0.5, v[152:153] op_sel_hi:[1,0,1]
	global_store_dwordx4 v[102:103], v[92:95], off nt
	global_store_dwordx4 v[102:103], v[88:91], off offset:16 nt
	v_cvt_pk_bf16_f32 v96, v92, v93
	v_mul_f32_e32 v93, v93, v93
	v_fmac_f32_e32 v93, v92, v92
	v_mul_f32_e32 v92, v95, v95
	v_cvt_pk_bf16_f32 v98, v88, v89
	v_fmac_f32_e32 v92, v94, v94
	v_mul_f32_e32 v89, v89, v89
	v_add_f32_e32 v92, v93, v92
	v_fmac_f32_e32 v89, v88, v88
	v_add_f32_e32 v88, v89, v92
	v_mul_f32_e32 v89, v91, v91
	v_fmac_f32_e32 v89, v90, v90
	v_pk_fma_f32 v[86:87], v[86:87], 0.5, v[150:151] op_sel_hi:[1,0,1]
	v_pk_fma_f32 v[84:85], v[84:85], 0.5, v[148:149] op_sel_hi:[1,0,1]
	v_cvt_pk_bf16_f32 v99, v90, v91
	v_add_f32_e32 v88, v89, v88
	v_mul_f32_e32 v89, v85, v85
	v_mul_f32_e32 v90, v87, v87
	v_pk_fma_f32 v[80:81], v[80:81], 0.5, v[144:145] op_sel_hi:[1,0,1]
	v_fmac_f32_e32 v89, v84, v84
	v_fmac_f32_e32 v90, v86, v86
	v_add_f32_e32 v89, v89, v90
	v_mul_f32_e32 v90, v81, v81
	v_pk_fma_f32 v[82:83], v[82:83], 0.5, v[146:147] op_sel_hi:[1,0,1]
	v_fmac_f32_e32 v90, v80, v80
	v_add_f32_e32 v89, v90, v89
	v_mul_f32_e32 v90, v83, v83
	v_fmac_f32_e32 v90, v82, v82
	v_add_f32_e32 v89, v90, v89
	v_add_f32_e32 v88, v88, v89
	ds_bpermute_b32 v89, v213, v88
	v_lshlrev_b64 v[100:101], 1, v[100:101]
	v_cvt_pk_bf16_f32 v97, v94, v95
	v_lshl_add_u64 v[104:105], s[80:81], 0, v[100:101]
	global_store_dwordx4 v[104:105], v[96:99], off
	global_store_dwordx4 v[102:103], v[84:87], off offset:512 nt
	global_store_dwordx4 v[102:103], v[80:83], off offset:528 nt
	v_or_b32_e32 v100, 0x100, v100
	v_cvt_pk_bf16_f32 v84, v84, v85
	v_cvt_pk_bf16_f32 v85, v86, v87
	v_cvt_pk_bf16_f32 v86, v80, v81
	s_waitcnt lgkmcnt(0)
	v_add_f32_e32 v80, v88, v89
	ds_bpermute_b32 v81, v212, v80
	v_cvt_pk_bf16_f32 v87, v82, v83
	v_lshl_add_u64 v[82:83], s[80:81], 0, v[100:101]
	global_store_dwordx4 v[82:83], v[84:87], off
	s_and_saveexec_b64 s[20:21], s[2:3]
	s_cbranch_execz .LBB0_294
	v_lshl_add_u64 v[82:83], v[200:201], 2, s[12:13]
	s_waitcnt lgkmcnt(0)
	v_add_f32_e32 v80, v80, v81
	global_atomic_add_f32 v[82:83], v80, off
; __device__ __forceinline__ unsigned cvtpk(float lo, float hi) { f32x2_t v = {lo, hi}; bf16x2_t b = __builtin_convertvector(v, bf16x2_t); return __builtin_bit_cast(unsigned, b); }
;     __device__ __forceinline__ void operator()(const pg8::f32x4 (&acc)[2][2][4][2], const pg8::Unit& u, int wr, int wc, int fr, int fq) const {
;     ...
;         for (int ai = 0; ai < 2; ++ai) {
;             pg8::f32x4 rv[4][2][2];
; #pragma unroll
;             for (int m = 0; m < 4; ++m)
; #pragma unroll
;                 for (int bj = 0; bj < 2; ++bj) { const size_t off = (size_t)(row0 + ai * 128 + m * 16) * DM + colb + bj * 128;
;                     rv[m][bj][0] = *(const pg8::f32x4*)(R + off); rv[m][bj][1] = *(const pg8::f32x4*)(R + off + 4); }
; #pragma unroll
;             for (int m = 0; m < 4; ++m) {
;                 const int row = row0 + ai * 128 + m * 16;
;                 float sq = 0.f;
; #pragma unroll
;                 for (int bj = 0; bj < 2; ++bj) {
;                     const size_t off = (size_t)row * DM + colb + bj * 128;
;                     const pg8::f32x4 v0 = rv[m][bj][0] + acc[ai][bj][m][0] * alpha, v1 = rv[m][bj][1] + acc[ai][bj][m][1] * alpha;
;                     *(pg8::f32x4*)(X + off) = v0; *(pg8::f32x4*)(X + off + 4) = v1;
;                     u32x4 w; w[0] = cvtpk(v0[0], v0[1]); w[1] = cvtpk(v0[2], v0[3]); w[2] = cvtpk(v1[0], v1[1]); w[3] = cvtpk(v1[2], v1[3]);
;                     *(u32x4*)(XB + off) = w;
;                     sq += (v0[0] * v0[0] + v0[1] * v0[1]) + (v0[2] * v0[2] + v0[3] * v0[3]) + (v1[0] * v1[0] + v1[1] * v1[1]) + (v1[2] * v1[2] + v1[3] * v1[3]);
;                 }
;                 sq += __shfl_xor(sq, 16); sq += __shfl_xor(sq, 32);
;                 if (fq == 0) atomicAdd(ssout + row, sq);
;             }
.LBB0_294:
	s_or_b64 exec, exec, s[20:21]
	s_waitcnt lgkmcnt(0)
	v_lshlrev_b64 v[80:81], 11, v[198:199]
	v_lshl_add_u64 v[84:85], v[80:81], 0, v[192:193]
	v_pk_fma_f32 v[78:79], v[78:79], 0.5, v[142:143] op_sel_hi:[1,0,1]
	v_pk_fma_f32 v[76:77], v[76:77], 0.5, v[140:141] op_sel_hi:[1,0,1]
	v_lshl_add_u64 v[86:87], v[84:85], 2, s[62:63]
	v_pk_fma_f32 v[74:75], v[74:75], 0.5, v[138:139] op_sel_hi:[1,0,1]
	v_pk_fma_f32 v[72:73], v[72:73], 0.5, v[136:137] op_sel_hi:[1,0,1]
	global_store_dwordx4 v[86:87], v[76:79], off nt
	global_store_dwordx4 v[86:87], v[72:75], off offset:16 nt
	v_cvt_pk_bf16_f32 v80, v76, v77
	v_mul_f32_e32 v77, v77, v77
	v_fmac_f32_e32 v77, v76, v76
	v_mul_f32_e32 v76, v79, v79
	v_cvt_pk_bf16_f32 v82, v72, v73
	v_fmac_f32_e32 v76, v78, v78
	v_mul_f32_e32 v73, v73, v73
	v_add_f32_e32 v76, v77, v76
	v_fmac_f32_e32 v73, v72, v72
	v_add_f32_e32 v72, v73, v76
	v_mul_f32_e32 v73, v75, v75
	v_fmac_f32_e32 v73, v74, v74
	v_pk_fma_f32 v[70:71], v[70:71], 0.5, v[134:135] op_sel_hi:[1,0,1]
	v_pk_fma_f32 v[68:69], v[68:69], 0.5, v[132:133] op_sel_hi:[1,0,1]
	v_cvt_pk_bf16_f32 v83, v74, v75
	v_add_f32_e32 v72, v73, v72
	v_mul_f32_e32 v73, v69, v69
	v_mul_f32_e32 v74, v71, v71
	v_pk_fma_f32 v[64:65], v[64:65], 0.5, v[128:129] op_sel_hi:[1,0,1]
	v_fmac_f32_e32 v73, v68, v68
	v_fmac_f32_e32 v74, v70, v70
	v_add_f32_e32 v73, v73, v74
	v_mul_f32_e32 v74, v65, v65
	v_pk_fma_f32 v[66:67], v[66:67], 0.5, v[130:131] op_sel_hi:[1,0,1]
	v_fmac_f32_e32 v74, v64, v64
	v_add_f32_e32 v73, v74, v73
	v_mul_f32_e32 v74, v67, v67
	v_fmac_f32_e32 v74, v66, v66
	v_add_f32_e32 v73, v74, v73
	v_add_f32_e32 v72, v72, v73
	ds_bpermute_b32 v73, v213, v72
	v_lshlrev_b64 v[84:85], 1, v[84:85]
	v_cvt_pk_bf16_f32 v81, v78, v79
	v_lshl_add_u64 v[88:89], s[80:81], 0, v[84:85]
	global_store_dwordx4 v[88:89], v[80:83], off
	global_store_dwordx4 v[86:87], v[68:71], off offset:512 nt
	global_store_dwordx4 v[86:87], v[64:67], off offset:528 nt
	v_or_b32_e32 v84, 0x100, v84
	v_cvt_pk_bf16_f32 v68, v68, v69
	v_cvt_pk_bf16_f32 v69, v70, v71
	v_cvt_pk_bf16_f32 v70, v64, v65
	s_waitcnt lgkmcnt(0)
	v_add_f32_e32 v64, v72, v73
	ds_bpermute_b32 v65, v212, v64
	v_cvt_pk_bf16_f32 v71, v66, v67
	v_lshl_add_u64 v[66:67], s[80:81], 0, v[84:85]
	global_store_dwordx4 v[66:67], v[68:71], off
	s_and_saveexec_b64 s[20:21], s[2:3]
	s_cbranch_execz .LBB0_296
	v_lshl_add_u64 v[66:67], v[198:199], 2, s[12:13]
	s_waitcnt lgkmcnt(0)
	v_add_f32_e32 v64, v64, v65
	global_atomic_add_f32 v[66:67], v64, off
.LBB0_296:
	s_or_b64 exec, exec, s[20:21]
	v_add_u32_e32 v118, 0x80, v194
	v_ashrrev_i32_e32 v119, 31, v118
	s_waitcnt lgkmcnt(0)
	v_lshlrev_b64 v[64:65], 13, v[118:119]
	v_lshl_add_u64 v[64:65], v[196:197], 0, v[64:65]
	global_load_dwordx4 v[120:123], v[64:65], off
	global_load_dwordx4 v[124:127], v[64:65], off offset:16
	global_load_dwordx4 v[128:131], v[64:65], off offset:512
	global_load_dwordx4 v[132:135], v[64:65], off offset:528
	v_add_u32_e32 v116, 0x90, v194
	v_add_u32_e32 v114, 0xa0, v194
	v_add_u32_e32 v112, 0xb0, v194
	v_ashrrev_i32_e32 v117, 31, v116
	v_ashrrev_i32_e32 v115, 31, v114
	v_ashrrev_i32_e32 v113, 31, v112
	v_lshlrev_b64 v[64:65], 13, v[116:117]
	v_lshlrev_b64 v[66:67], 13, v[114:115]
	v_lshlrev_b64 v[68:69], 13, v[112:113]
	v_lshl_add_u64 v[64:65], v[196:197], 0, v[64:65]
	v_lshl_add_u64 v[66:67], v[196:197], 0, v[66:67]
	v_lshl_add_u64 v[68:69], v[196:197], 0, v[68:69]
	global_load_dwordx4 v[104:107], v[64:65], off offset:16
	global_load_dwordx4 v[108:111], v[64:65], off
	global_load_dwordx4 v[96:99], v[64:65], off offset:528
	global_load_dwordx4 v[100:103], v[64:65], off offset:512
	global_load_dwordx4 v[88:91], v[66:67], off offset:16
	global_load_dwordx4 v[92:95], v[66:67], off
	global_load_dwordx4 v[80:83], v[66:67], off offset:528
	global_load_dwordx4 v[84:87], v[66:67], off offset:512
	global_load_dwordx4 v[72:75], v[68:69], off offset:16
	global_load_dwordx4 v[76:79], v[68:69], off
	s_nop 0
	global_load_dwordx4 v[64:67], v[68:69], off offset:528
	s_nop 0
	global_load_dwordx4 v[68:71], v[68:69], off offset:512
	v_lshlrev_b64 v[136:137], 11, v[118:119]
	v_lshl_add_u64 v[136:137], v[136:137], 0, v[192:193]
	v_lshl_add_u64 v[138:139], v[136:137], 2, s[62:63]
	v_lshlrev_b64 v[136:137], 1, v[136:137]
	v_lshl_add_u64 v[140:141], s[80:81], 0, v[136:137]
	v_or_b32_e32 v136, 0x100, v136
	s_waitcnt vmcnt(15)
	v_pk_fma_f32 v[62:63], v[62:63], 0.5, v[122:123] op_sel_hi:[1,0,1]
	v_pk_fma_f32 v[60:61], v[60:61], 0.5, v[120:121] op_sel_hi:[1,0,1]
	s_waitcnt vmcnt(13)
	v_pk_fma_f32 v[54:55], v[54:55], 0.5, v[130:131] op_sel_hi:[1,0,1]
	v_pk_fma_f32 v[52:53], v[52:53], 0.5, v[128:129] op_sel_hi:[1,0,1]
	v_pk_fma_f32 v[58:59], v[58:59], 0.5, v[126:127] op_sel_hi:[1,0,1]
	v_pk_fma_f32 v[56:57], v[56:57], 0.5, v[124:125] op_sel_hi:[1,0,1]
	s_waitcnt vmcnt(12)
	v_pk_fma_f32 v[48:49], v[48:49], 0.5, v[132:133] op_sel_hi:[1,0,1]
	global_store_dwordx4 v[138:139], v[60:63], off nt
	global_store_dwordx4 v[138:139], v[56:59], off offset:16 nt
	v_cvt_pk_bf16_f32 v120, v60, v61
	v_cvt_pk_bf16_f32 v121, v62, v63
	v_mul_f32_e32 v61, v61, v61
	v_mul_f32_e32 v63, v63, v63
	v_mul_f32_e32 v124, v53, v53
	v_mul_f32_e32 v125, v55, v55
	v_pk_fma_f32 v[50:51], v[50:51], 0.5, v[134:135] op_sel_hi:[1,0,1]
	v_cvt_pk_bf16_f32 v122, v56, v57
	v_cvt_pk_bf16_f32 v123, v58, v59
	v_mul_f32_e32 v57, v57, v57
	v_mul_f32_e32 v59, v59, v59
	v_mul_f32_e32 v126, v49, v49
	v_fmac_f32_e32 v61, v60, v60
	v_fmac_f32_e32 v63, v62, v62
	v_fmac_f32_e32 v124, v52, v52
	v_fmac_f32_e32 v125, v54, v54
	v_mul_f32_e32 v127, v51, v51
	v_fmac_f32_e32 v57, v56, v56
	v_fmac_f32_e32 v59, v58, v58
	v_fmac_f32_e32 v126, v48, v48
	v_add_f32_e32 v56, v61, v63
	v_add_f32_e32 v58, v124, v125
	v_fmac_f32_e32 v127, v50, v50
	v_add_f32_e32 v56, v57, v56
	v_add_f32_e32 v57, v126, v58
	v_add_f32_e32 v56, v59, v56
	v_add_f32_e32 v57, v127, v57
	v_add_f32_e32 v56, v56, v57
	ds_bpermute_b32 v57, v213, v56
	global_store_dwordx4 v[140:141], v[120:123], off
	global_store_dwordx4 v[138:139], v[52:55], off offset:512 nt
	global_store_dwordx4 v[138:139], v[48:51], off offset:528 nt
	s_nop 0
	v_cvt_pk_bf16_f32 v52, v52, v53
	v_cvt_pk_bf16_f32 v53, v54, v55
	v_cvt_pk_bf16_f32 v54, v48, v49
	s_waitcnt lgkmcnt(0)
	v_add_f32_e32 v48, v56, v57
	ds_bpermute_b32 v49, v212, v48
	v_cvt_pk_bf16_f32 v55, v50, v51
	v_lshl_add_u64 v[50:51], s[80:81], 0, v[136:137]
	global_store_dwordx4 v[50:51], v[52:55], off
	s_and_saveexec_b64 s[20:21], s[2:3]
	s_cbranch_execz .LBB0_298
	v_lshl_add_u64 v[50:51], v[118:119], 2, s[12:13]
	s_waitcnt lgkmcnt(0)
	v_add_f32_e32 v48, v48, v49
	global_atomic_add_f32 v[50:51], v48, off
; __device__ __forceinline__ unsigned cvtpk(float lo, float hi) { f32x2_t v = {lo, hi}; bf16x2_t b = __builtin_convertvector(v, bf16x2_t); return __builtin_bit_cast(unsigned, b); }
;     __device__ __forceinline__ void operator()(const pg8::f32x4 (&acc)[2][2][4][2], const pg8::Unit& u, int wr, int wc, int fr, int fq) const {
;     ...
;             for (int m = 0; m < 4; ++m) {
;                 const int row = row0 + ai * 128 + m * 16;
;                 float sq = 0.f;
; #pragma unroll
;                 for (int bj = 0; bj < 2; ++bj) {
;                     const size_t off = (size_t)row * DM + colb + bj * 128;
;                     const pg8::f32x4 v0 = rv[m][bj][0] + acc[ai][bj][m][0] * alpha, v1 = rv[m][bj][1] + acc[ai][bj][m][1] * alpha;
;                     *(pg8::f32x4*)(X + off) = v0; *(pg8::f32x4*)(X + off + 4) = v1;
;                     u32x4 w; w[0] = cvtpk(v0[0], v0[1]); w[1] = cvtpk(v0[2], v0[3]); w[2] = cvtpk(v1[0], v1[1]); w[3] = cvtpk(v1[2], v1[3]);
;                     *(u32x4*)(XB + off) = w;
;                     sq += (v0[0] * v0[0] + v0[1] * v0[1]) + (v0[2] * v0[2] + v0[3] * v0[3]) + (v1[0] * v1[0] + v1[1] * v1[1]) + (v1[2] * v1[2] + v1[3] * v1[3]);
;                 }
;                 sq += __shfl_xor(sq, 16); sq += __shfl_xor(sq, 32);
;                 if (fq == 0) atomicAdd(ssout + row, sq);
;             }
.LBB0_298:
	s_or_b64 exec, exec, s[20:21]
	s_waitcnt lgkmcnt(0)
	v_lshlrev_b64 v[48:49], 11, v[116:117]
	v_lshl_add_u64 v[52:53], v[48:49], 0, v[192:193]
	s_waitcnt vmcnt(16)
	v_pk_fma_f32 v[46:47], v[46:47], 0.5, v[110:111] op_sel_hi:[1,0,1]
	v_pk_fma_f32 v[44:45], v[44:45], 0.5, v[108:109] op_sel_hi:[1,0,1]
	v_lshl_add_u64 v[54:55], v[52:53], 2, s[62:63]
	v_pk_fma_f32 v[42:43], v[42:43], 0.5, v[106:107] op_sel_hi:[1,0,1]
	v_pk_fma_f32 v[40:41], v[40:41], 0.5, v[104:105] op_sel_hi:[1,0,1]
	global_store_dwordx4 v[54:55], v[44:47], off nt
	global_store_dwordx4 v[54:55], v[40:43], off offset:16 nt
	v_cvt_pk_bf16_f32 v48, v44, v45
	v_mul_f32_e32 v45, v45, v45
	v_fmac_f32_e32 v45, v44, v44
	v_mul_f32_e32 v44, v47, v47
	v_cvt_pk_bf16_f32 v50, v40, v41
	v_fmac_f32_e32 v44, v46, v46
	v_mul_f32_e32 v41, v41, v41
	v_add_f32_e32 v44, v45, v44
	v_fmac_f32_e32 v41, v40, v40
	v_add_f32_e32 v40, v41, v44
	v_mul_f32_e32 v41, v43, v43
	v_fmac_f32_e32 v41, v42, v42
	s_waitcnt vmcnt(16)
	v_pk_fma_f32 v[38:39], v[38:39], 0.5, v[102:103] op_sel_hi:[1,0,1]
	v_pk_fma_f32 v[36:37], v[36:37], 0.5, v[100:101] op_sel_hi:[1,0,1]
	v_cvt_pk_bf16_f32 v51, v42, v43
	v_add_f32_e32 v40, v41, v40
	v_mul_f32_e32 v41, v37, v37
	v_mul_f32_e32 v42, v39, v39
	v_pk_fma_f32 v[32:33], v[32:33], 0.5, v[96:97] op_sel_hi:[1,0,1]
	v_fmac_f32_e32 v41, v36, v36
	v_fmac_f32_e32 v42, v38, v38
	v_add_f32_e32 v41, v41, v42
	v_mul_f32_e32 v42, v33, v33
	v_pk_fma_f32 v[34:35], v[34:35], 0.5, v[98:99] op_sel_hi:[1,0,1]
	v_fmac_f32_e32 v42, v32, v32
	v_add_f32_e32 v41, v42, v41
	v_mul_f32_e32 v42, v35, v35
	v_fmac_f32_e32 v42, v34, v34
	v_add_f32_e32 v41, v42, v41
	v_add_f32_e32 v40, v40, v41
	ds_bpermute_b32 v41, v213, v40
	v_lshlrev_b64 v[52:53], 1, v[52:53]
	v_cvt_pk_bf16_f32 v49, v46, v47
	v_lshl_add_u64 v[56:57], s[80:81], 0, v[52:53]
	global_store_dwordx4 v[56:57], v[48:51], off
	global_store_dwordx4 v[54:55], v[36:39], off offset:512 nt
	global_store_dwordx4 v[54:55], v[32:35], off offset:528 nt
	v_or_b32_e32 v52, 0x100, v52
	v_cvt_pk_bf16_f32 v36, v36, v37
	v_cvt_pk_bf16_f32 v37, v38, v39
	v_cvt_pk_bf16_f32 v38, v32, v33
	s_waitcnt lgkmcnt(0)
	v_add_f32_e32 v32, v40, v41
	ds_bpermute_b32 v33, v212, v32
	v_cvt_pk_bf16_f32 v39, v34, v35
	v_lshl_add_u64 v[34:35], s[80:81], 0, v[52:53]
	global_store_dwordx4 v[34:35], v[36:39], off
	s_and_saveexec_b64 s[20:21], s[2:3]
	s_cbranch_execz .LBB0_300
	v_lshl_add_u64 v[34:35], v[116:117], 2, s[12:13]
	s_waitcnt lgkmcnt(0)
	v_add_f32_e32 v32, v32, v33
	global_atomic_add_f32 v[34:35], v32, off
; __device__ __forceinline__ unsigned cvtpk(float lo, float hi) { f32x2_t v = {lo, hi}; bf16x2_t b = __builtin_convertvector(v, bf16x2_t); return __builtin_bit_cast(unsigned, b); }
;     __device__ __forceinline__ void operator()(const pg8::f32x4 (&acc)[2][2][4][2], const pg8::Unit& u, int wr, int wc, int fr, int fq) const {
;     ...
;             for (int m = 0; m < 4; ++m) {
;                 const int row = row0 + ai * 128 + m * 16;
;                 float sq = 0.f;
; #pragma unroll
;                 for (int bj = 0; bj < 2; ++bj) {
;                     const size_t off = (size_t)row * DM + colb + bj * 128;
;                     const pg8::f32x4 v0 = rv[m][bj][0] + acc[ai][bj][m][0] * alpha, v1 = rv[m][bj][1] + acc[ai][bj][m][1] * alpha;
;                     *(pg8::f32x4*)(X + off) = v0; *(pg8::f32x4*)(X + off + 4) = v1;
;                     u32x4 w; w[0] = cvtpk(v0[0], v0[1]); w[1] = cvtpk(v0[2], v0[3]); w[2] = cvtpk(v1[0], v1[1]); w[3] = cvtpk(v1[2], v1[3]);
;                     *(u32x4*)(XB + off) = w;
;                     sq += (v0[0] * v0[0] + v0[1] * v0[1]) + (v0[2] * v0[2] + v0[3] * v0[3]) + (v1[0] * v1[0] + v1[1] * v1[1]) + (v1[2] * v1[2] + v1[3] * v1[3]);
;                 }
;                 sq += __shfl_xor(sq, 16); sq += __shfl_xor(sq, 32);
;                 if (fq == 0) atomicAdd(ssout + row, sq);
;             }
.LBB0_300:
	s_or_b64 exec, exec, s[20:21]
	s_waitcnt lgkmcnt(0)
	v_lshlrev_b64 v[32:33], 11, v[114:115]
	v_lshl_add_u64 v[36:37], v[32:33], 0, v[192:193]
	s_waitcnt vmcnt(18)
	v_pk_fma_f32 v[30:31], v[30:31], 0.5, v[94:95] op_sel_hi:[1,0,1]
	v_pk_fma_f32 v[28:29], v[28:29], 0.5, v[92:93] op_sel_hi:[1,0,1]
	v_lshl_add_u64 v[38:39], v[36:37], 2, s[62:63]
	v_pk_fma_f32 v[26:27], v[26:27], 0.5, v[90:91] op_sel_hi:[1,0,1]
	v_pk_fma_f32 v[24:25], v[24:25], 0.5, v[88:89] op_sel_hi:[1,0,1]
	global_store_dwordx4 v[38:39], v[28:31], off nt
	global_store_dwordx4 v[38:39], v[24:27], off offset:16 nt
	v_cvt_pk_bf16_f32 v32, v28, v29
	v_mul_f32_e32 v29, v29, v29
	v_fmac_f32_e32 v29, v28, v28
	v_mul_f32_e32 v28, v31, v31
	v_cvt_pk_bf16_f32 v34, v24, v25
	v_fmac_f32_e32 v28, v30, v30
	v_mul_f32_e32 v25, v25, v25
	v_add_f32_e32 v28, v29, v28
	v_fmac_f32_e32 v25, v24, v24
	v_add_f32_e32 v24, v25, v28
	v_mul_f32_e32 v25, v27, v27
	v_fmac_f32_e32 v25, v26, v26
	s_waitcnt vmcnt(18)
	v_pk_fma_f32 v[22:23], v[22:23], 0.5, v[86:87] op_sel_hi:[1,0,1]
	v_pk_fma_f32 v[20:21], v[20:21], 0.5, v[84:85] op_sel_hi:[1,0,1]
	v_cvt_pk_bf16_f32 v35, v26, v27
	v_add_f32_e32 v24, v25, v24
	v_mul_f32_e32 v25, v21, v21
	v_mul_f32_e32 v26, v23, v23
	v_pk_fma_f32 v[16:17], v[16:17], 0.5, v[80:81] op_sel_hi:[1,0,1]
	v_fmac_f32_e32 v25, v20, v20
	v_fmac_f32_e32 v26, v22, v22
	v_add_f32_e32 v25, v25, v26
	v_mul_f32_e32 v26, v17, v17
	v_pk_fma_f32 v[18:19], v[18:19], 0.5, v[82:83] op_sel_hi:[1,0,1]
	v_fmac_f32_e32 v26, v16, v16
	v_add_f32_e32 v25, v26, v25
	v_mul_f32_e32 v26, v19, v19
	v_fmac_f32_e32 v26, v18, v18
	v_add_f32_e32 v25, v26, v25
	v_add_f32_e32 v24, v24, v25
	ds_bpermute_b32 v25, v213, v24
	v_lshlrev_b64 v[36:37], 1, v[36:37]
	v_cvt_pk_bf16_f32 v33, v30, v31
	v_lshl_add_u64 v[40:41], s[80:81], 0, v[36:37]
	global_store_dwordx4 v[40:41], v[32:35], off
	global_store_dwordx4 v[38:39], v[20:23], off offset:512 nt
	global_store_dwordx4 v[38:39], v[16:19], off offset:528 nt
	v_or_b32_e32 v36, 0x100, v36
	v_cvt_pk_bf16_f32 v20, v20, v21
	v_cvt_pk_bf16_f32 v21, v22, v23
	v_cvt_pk_bf16_f32 v22, v16, v17
	s_waitcnt lgkmcnt(0)
	v_add_f32_e32 v16, v24, v25
	ds_bpermute_b32 v17, v212, v16
	v_cvt_pk_bf16_f32 v23, v18, v19
	v_lshl_add_u64 v[18:19], s[80:81], 0, v[36:37]
	global_store_dwordx4 v[18:19], v[20:23], off
	s_and_saveexec_b64 s[20:21], s[2:3]
	s_cbranch_execz .LBB0_302
	v_lshl_add_u64 v[18:19], v[114:115], 2, s[12:13]
	s_waitcnt lgkmcnt(0)
	v_add_f32_e32 v16, v16, v17
	global_atomic_add_f32 v[18:19], v16, off
.LBB0_302:
	s_or_b64 exec, exec, s[20:21]
	s_waitcnt lgkmcnt(0)
	v_lshlrev_b64 v[16:17], 11, v[112:113]
	v_lshl_add_u64 v[20:21], v[16:17], 0, v[192:193]
	s_waitcnt vmcnt(20)
	v_pk_fma_f32 v[14:15], v[14:15], 0.5, v[78:79] op_sel_hi:[1,0,1]
	v_pk_fma_f32 v[12:13], v[12:13], 0.5, v[76:77] op_sel_hi:[1,0,1]
	v_lshl_add_u64 v[22:23], v[20:21], 2, s[62:63]
	v_pk_fma_f32 v[10:11], v[10:11], 0.5, v[74:75] op_sel_hi:[1,0,1]
	v_pk_fma_f32 v[8:9], v[8:9], 0.5, v[72:73] op_sel_hi:[1,0,1]
	global_store_dwordx4 v[22:23], v[12:15], off nt
	global_store_dwordx4 v[22:23], v[8:11], off offset:16 nt
	v_cvt_pk_bf16_f32 v16, v12, v13
	v_mul_f32_e32 v13, v13, v13
	v_fmac_f32_e32 v13, v12, v12
	v_mul_f32_e32 v12, v15, v15
	v_cvt_pk_bf16_f32 v18, v8, v9
	v_fmac_f32_e32 v12, v14, v14
	v_mul_f32_e32 v9, v9, v9
	v_add_f32_e32 v12, v13, v12
	v_fmac_f32_e32 v9, v8, v8
	v_add_f32_e32 v8, v9, v12
	v_mul_f32_e32 v9, v11, v11
	v_fmac_f32_e32 v9, v10, v10
	s_waitcnt vmcnt(20)
	v_pk_fma_f32 v[6:7], v[6:7], 0.5, v[70:71] op_sel_hi:[1,0,1]
	v_pk_fma_f32 v[4:5], v[4:5], 0.5, v[68:69] op_sel_hi:[1,0,1]
	v_cvt_pk_bf16_f32 v19, v10, v11
	v_add_f32_e32 v8, v9, v8
	v_mul_f32_e32 v9, v5, v5
	v_mul_f32_e32 v10, v7, v7
	v_pk_fma_f32 v[0:1], v[0:1], 0.5, v[64:65] op_sel_hi:[1,0,1]
	v_fmac_f32_e32 v9, v4, v4
	v_fmac_f32_e32 v10, v6, v6
	v_add_f32_e32 v9, v9, v10
	v_mul_f32_e32 v10, v1, v1
	v_pk_fma_f32 v[2:3], v[2:3], 0.5, v[66:67] op_sel_hi:[1,0,1]
	v_fmac_f32_e32 v10, v0, v0
	v_add_f32_e32 v9, v10, v9
	v_mul_f32_e32 v10, v3, v3
	v_fmac_f32_e32 v10, v2, v2
	v_add_f32_e32 v9, v10, v9
	v_add_f32_e32 v8, v8, v9
	ds_bpermute_b32 v9, v213, v8
	v_lshlrev_b64 v[20:21], 1, v[20:21]
	v_cvt_pk_bf16_f32 v17, v14, v15
	v_lshl_add_u64 v[24:25], s[80:81], 0, v[20:21]
	global_store_dwordx4 v[24:25], v[16:19], off
	global_store_dwordx4 v[22:23], v[4:7], off offset:512 nt
	global_store_dwordx4 v[22:23], v[0:3], off offset:528 nt
	v_or_b32_e32 v20, 0x100, v20
	v_cvt_pk_bf16_f32 v4, v4, v5
	v_cvt_pk_bf16_f32 v5, v6, v7
	v_cvt_pk_bf16_f32 v6, v0, v1
	s_waitcnt lgkmcnt(0)
	v_add_f32_e32 v0, v8, v9
	ds_bpermute_b32 v1, v212, v0
	v_cvt_pk_bf16_f32 v7, v2, v3
	v_lshl_add_u64 v[2:3], s[80:81], 0, v[20:21]
	global_store_dwordx4 v[2:3], v[4:7], off
	s_and_saveexec_b64 s[20:21], s[2:3]
	s_cbranch_execz .LBB0_304
	v_lshl_add_u64 v[2:3], v[112:113], 2, s[12:13]
	s_waitcnt lgkmcnt(0)
	v_add_f32_e32 v0, v0, v1
	global_atomic_add_f32 v[2:3], v0, off

; __device__ __forceinline__ unsigned cvtpk(float lo, float hi) { f32x2_t v = {lo, hi}; bf16x2_t b = __builtin_convertvector(v, bf16x2_t); return __builtin_bit_cast(unsigned, b); }
;     __device__ __forceinline__ void operator()(const pg8::f32x4 (&acc)[2][2][4][2], const pg8::Unit& u, int wr, int wc, int fr, int fq) const {
;         const int row0 = u.pm * 256 + wr * 64 + fr, colb = u.pn * 256 + wc * 32 + 8 * fq;
; #pragma unroll
;         for (int ai = 0; ai < 2; ++ai) {
;             pg8::f32x4 rv[4][2][2];
; #pragma unroll
;             for (int m = 0; m < 4; ++m)
; #pragma unroll
;                 for (int bj = 0; bj < 2; ++bj) { const size_t off = (size_t)(row0 + ai * 128 + m * 16) * DM + colb + bj * 128;
;                     rv[m][bj][0] = *(const pg8::f32x4*)(R + off); rv[m][bj][1] = *(const pg8::f32x4*)(R + off + 4); }
; #pragma unroll
;             for (int m = 0; m < 4; ++m) {
;                 const int row = row0 + ai * 128 + m * 16;
;                 float sq = 0.f;
; #pragma unroll
;                 for (int bj = 0; bj < 2; ++bj) {
;                     const size_t off = (size_t)row * DM + colb + bj * 128;
;                     const pg8::f32x4 v0 = rv[m][bj][0] + acc[ai][bj][m][0] * alpha, v1 = rv[m][bj][1] + acc[ai][bj][m][1] * alpha;
;                     *(pg8::f32x4*)(X + off) = v0; *(pg8::f32x4*)(X + off + 4) = v1;
;                     u32x4 w; w[0] = cvtpk(v0[0], v0[1]); w[1] = cvtpk(v0[2], v0[3]); w[2] = cvtpk(v1[0], v1[1]); w[3] = cvtpk(v1[2], v1[3]);
;                     *(u32x4*)(XB + off) = w;
;                     sq += (v0[0] * v0[0] + v0[1] * v0[1]) + (v0[2] * v0[2] + v0[3] * v0[3]) + (v1[0] * v1[0] + v1[1] * v1[1]) + (v1[2] * v1[2] + v1[3] * v1[3]);
;                 }
;                 sq += __shfl_xor(sq, 16); sq += __shfl_xor(sq, 32);
;                 if (fq == 0) atomicAdd(ssout + row, sq);
;             }
.LBB0_996:
	v_lshl_add_u32 v194, s22, 8, v210
	v_lshl_or_b32 v192, s24, 8, v212
	v_ashrrev_i32_e32 v193, 31, v192
	v_ashrrev_i32_e32 v195, 31, v194
	v_lshl_add_u64 v[196:197], v[192:193], 2, s[62:63]
	v_lshlrev_b64 v[128:129], 13, v[194:195]
	v_lshl_add_u64 v[238:239], v[196:197], 0, v[128:129]
	global_load_dwordx4 v[222:225], v[238:239], off
	global_load_dwordx4 v[226:229], v[238:239], off offset:16
	global_load_dwordx4 v[230:233], v[238:239], off offset:512
	global_load_dwordx4 v[234:237], v[238:239], off offset:528
	v_or_b32_e32 v206, 16, v194
	v_or_b32_e32 v202, 32, v194
	v_or_b32_e32 v198, 48, v194
	v_ashrrev_i32_e32 v207, 31, v206
	v_ashrrev_i32_e32 v203, 31, v202
	v_ashrrev_i32_e32 v199, 31, v198
	v_lshlrev_b64 v[128:129], 13, v[206:207]
	v_lshlrev_b64 v[130:131], 13, v[202:203]
	v_lshlrev_b64 v[132:133], 13, v[198:199]
	v_lshl_add_u64 v[208:209], v[196:197], 0, v[128:129]
	v_lshl_add_u64 v[204:205], v[196:197], 0, v[130:131]
	v_lshl_add_u64 v[200:201], v[196:197], 0, v[132:133]
	global_load_dwordx4 v[168:171], v[208:209], off offset:16
	global_load_dwordx4 v[172:175], v[208:209], off
	global_load_dwordx4 v[160:163], v[208:209], off offset:528
	global_load_dwordx4 v[164:167], v[208:209], off offset:512
	global_load_dwordx4 v[152:155], v[204:205], off offset:16
	global_load_dwordx4 v[156:159], v[204:205], off
	global_load_dwordx4 v[144:147], v[204:205], off offset:528
	global_load_dwordx4 v[148:151], v[204:205], off offset:512
	global_load_dwordx4 v[136:139], v[200:201], off offset:16
	global_load_dwordx4 v[140:143], v[200:201], off
	global_load_dwordx4 v[128:131], v[200:201], off offset:528
	global_load_dwordx4 v[132:135], v[200:201], off offset:512
	v_and_b32_e32 v218, 64, v216
	v_xor_b32_e32 v217, 16, v216
	v_add_u32_e32 v218, 64, v218
	v_xor_b32_e32 v219, 32, v216
	v_cmp_lt_i32_e32 vcc, v217, v218
	v_lshlrev_b64 v[240:241], 11, v[194:195]
	v_lshl_add_u64 v[240:241], v[240:241], 0, v[192:193]
	v_cndmask_b32_e32 v217, v216, v217, vcc
	v_cmp_lt_i32_e32 vcc, v219, v218
	v_lshlrev_b32_e32 v218, 2, v217
	v_lshlrev_b64 v[240:241], 1, v[240:241]
	v_cndmask_b32_e32 v219, v216, v219, vcc
	v_lshlrev_b32_e32 v217, 2, v219
	v_lshl_add_u64 v[242:243], s[80:81], 0, v[240:241]
	v_or_b32_e32 v240, 0x100, v240
	s_waitcnt vmcnt(0)
	v_pk_add_f32 v[126:127], v[126:127], v[224:225]
	v_pk_add_f32 v[124:125], v[124:125], v[222:223]
	v_pk_add_f32 v[118:119], v[118:119], v[232:233]
	v_pk_add_f32 v[116:117], v[116:117], v[230:231]
	v_pk_add_f32 v[122:123], v[122:123], v[228:229]
	v_pk_add_f32 v[120:121], v[120:121], v[226:227]
	v_pk_add_f32 v[112:113], v[112:113], v[234:235]
	global_store_dwordx4 v[238:239], v[124:127], off nt
	global_store_dwordx4 v[238:239], v[120:123], off offset:16 nt
	v_cvt_pk_bf16_f32 v222, v124, v125
	v_cvt_pk_bf16_f32 v223, v126, v127
	v_mul_f32_e32 v125, v125, v125
	v_mul_f32_e32 v127, v127, v127
	v_mul_f32_e32 v219, v117, v117
	v_mul_f32_e32 v221, v119, v119
	v_pk_add_f32 v[114:115], v[114:115], v[236:237]
	v_cvt_pk_bf16_f32 v224, v120, v121
	v_cvt_pk_bf16_f32 v225, v122, v123
	v_mul_f32_e32 v121, v121, v121
	v_mul_f32_e32 v123, v123, v123
	v_mul_f32_e32 v226, v113, v113
	v_fmac_f32_e32 v125, v124, v124
	v_fmac_f32_e32 v127, v126, v126
	v_fmac_f32_e32 v219, v116, v116
	v_fmac_f32_e32 v221, v118, v118
	v_mul_f32_e32 v227, v115, v115
	v_fmac_f32_e32 v121, v120, v120
	v_fmac_f32_e32 v123, v122, v122
	v_fmac_f32_e32 v226, v112, v112
	v_add_f32_e32 v120, v125, v127
	v_add_f32_e32 v122, v219, v221
	v_fmac_f32_e32 v227, v114, v114
	v_add_f32_e32 v120, v121, v120
	v_add_f32_e32 v121, v226, v122
	v_add_f32_e32 v120, v123, v120
	v_add_f32_e32 v121, v227, v121
	v_add_f32_e32 v120, v120, v121
	ds_bpermute_b32 v121, v218, v120
	global_store_dwordx4 v[242:243], v[222:225], off
	global_store_dwordx4 v[238:239], v[116:119], off offset:512 nt
	global_store_dwordx4 v[238:239], v[112:115], off offset:528 nt
	s_nop 0
	v_cvt_pk_bf16_f32 v116, v116, v117
	v_cvt_pk_bf16_f32 v117, v118, v119
	v_cvt_pk_bf16_f32 v118, v112, v113
	s_waitcnt lgkmcnt(0)
	v_add_f32_e32 v112, v120, v121
	ds_bpermute_b32 v113, v217, v112
	v_cvt_pk_bf16_f32 v119, v114, v115
	v_lshl_add_u64 v[114:115], s[80:81], 0, v[240:241]
	global_store_dwordx4 v[114:115], v[116:119], off
	s_and_saveexec_b64 s[22:23], s[0:1]
	s_cbranch_execz .LBB0_998
	v_lshl_add_u64 v[114:115], v[194:195], 2, s[8:9]
	s_waitcnt lgkmcnt(0)
	v_add_f32_e32 v112, v112, v113
	global_atomic_add_f32 v[114:115], v112, off
.LBB0_998:
	s_or_b64 exec, exec, s[22:23]
	s_waitcnt lgkmcnt(0)
	v_lshlrev_b64 v[112:113], 11, v[206:207]
	v_pk_add_f32 v[110:111], v[110:111], v[174:175]
	v_pk_add_f32 v[108:109], v[108:109], v[172:173]
	v_lshl_add_u64 v[116:117], v[112:113], 0, v[192:193]
	v_pk_add_f32 v[106:107], v[106:107], v[170:171]
	v_pk_add_f32 v[104:105], v[104:105], v[168:169]
	global_store_dwordx4 v[208:209], v[108:111], off nt
	global_store_dwordx4 v[208:209], v[104:107], off offset:16 nt
	v_cvt_pk_bf16_f32 v112, v108, v109
	v_mul_f32_e32 v109, v109, v109
	v_fmac_f32_e32 v109, v108, v108
	v_mul_f32_e32 v108, v111, v111
	v_cvt_pk_bf16_f32 v114, v104, v105
	v_fmac_f32_e32 v108, v110, v110
	v_mul_f32_e32 v105, v105, v105
	v_add_f32_e32 v108, v109, v108
	v_fmac_f32_e32 v105, v104, v104
	v_add_f32_e32 v104, v105, v108
	v_mul_f32_e32 v105, v107, v107
	v_fmac_f32_e32 v105, v106, v106
	v_pk_add_f32 v[102:103], v[102:103], v[166:167]
	v_pk_add_f32 v[100:101], v[100:101], v[164:165]
	v_cvt_pk_bf16_f32 v115, v106, v107
	v_add_f32_e32 v104, v105, v104
	v_mul_f32_e32 v105, v101, v101
	v_mul_f32_e32 v106, v103, v103
	v_pk_add_f32 v[96:97], v[96:97], v[160:161]
	v_fmac_f32_e32 v105, v100, v100
	v_fmac_f32_e32 v106, v102, v102
	v_add_f32_e32 v105, v105, v106
	v_mul_f32_e32 v106, v97, v97
	v_pk_add_f32 v[98:99], v[98:99], v[162:163]
	v_fmac_f32_e32 v106, v96, v96
	v_add_f32_e32 v105, v106, v105
	v_mul_f32_e32 v106, v99, v99
	v_fmac_f32_e32 v106, v98, v98
	v_add_f32_e32 v105, v106, v105
	v_add_f32_e32 v104, v104, v105
	ds_bpermute_b32 v105, v218, v104
	v_lshlrev_b64 v[116:117], 1, v[116:117]
	v_cvt_pk_bf16_f32 v113, v110, v111
	v_lshl_add_u64 v[118:119], s[80:81], 0, v[116:117]
	global_store_dwordx4 v[118:119], v[112:115], off
	global_store_dwordx4 v[208:209], v[100:103], off offset:512 nt
	global_store_dwordx4 v[208:209], v[96:99], off offset:528 nt
	v_or_b32_e32 v116, 0x100, v116
	v_cvt_pk_bf16_f32 v100, v100, v101
	v_cvt_pk_bf16_f32 v101, v102, v103
	v_cvt_pk_bf16_f32 v102, v96, v97
	s_waitcnt lgkmcnt(0)
	v_add_f32_e32 v96, v104, v105
	ds_bpermute_b32 v97, v217, v96
	v_cvt_pk_bf16_f32 v103, v98, v99
	v_lshl_add_u64 v[98:99], s[80:81], 0, v[116:117]
	global_store_dwordx4 v[98:99], v[100:103], off
	s_and_saveexec_b64 s[22:23], s[0:1]
	s_cbranch_execz .LBB0_1000
	v_lshl_add_u64 v[98:99], v[206:207], 2, s[8:9]
	s_waitcnt lgkmcnt(0)
	v_add_f32_e32 v96, v96, v97
	global_atomic_add_f32 v[98:99], v96, off
; __device__ __forceinline__ unsigned cvtpk(float lo, float hi) { f32x2_t v = {lo, hi}; bf16x2_t b = __builtin_convertvector(v, bf16x2_t); return __builtin_bit_cast(unsigned, b); }
;     __device__ __forceinline__ void operator()(const pg8::f32x4 (&acc)[2][2][4][2], const pg8::Unit& u, int wr, int wc, int fr, int fq) const {
;     ...
;             for (int m = 0; m < 4; ++m) {
;                 const int row = row0 + ai * 128 + m * 16;
;                 float sq = 0.f;
; #pragma unroll
;                 for (int bj = 0; bj < 2; ++bj) {
;                     const size_t off = (size_t)row * DM + colb + bj * 128;
;                     const pg8::f32x4 v0 = rv[m][bj][0] + acc[ai][bj][m][0] * alpha, v1 = rv[m][bj][1] + acc[ai][bj][m][1] * alpha;
;                     *(pg8::f32x4*)(X + off) = v0; *(pg8::f32x4*)(X + off + 4) = v1;
;                     u32x4 w; w[0] = cvtpk(v0[0], v0[1]); w[1] = cvtpk(v0[2], v0[3]); w[2] = cvtpk(v1[0], v1[1]); w[3] = cvtpk(v1[2], v1[3]);
;                     *(u32x4*)(XB + off) = w;
;                     sq += (v0[0] * v0[0] + v0[1] * v0[1]) + (v0[2] * v0[2] + v0[3] * v0[3]) + (v1[0] * v1[0] + v1[1] * v1[1]) + (v1[2] * v1[2] + v1[3] * v1[3]);
;                 }
;                 sq += __shfl_xor(sq, 16); sq += __shfl_xor(sq, 32);
;                 if (fq == 0) atomicAdd(ssout + row, sq);
;             }
.LBB0_1000:
	s_or_b64 exec, exec, s[22:23]
	s_waitcnt lgkmcnt(0)
	v_lshlrev_b64 v[96:97], 11, v[202:203]
	v_pk_add_f32 v[94:95], v[94:95], v[158:159]
	v_pk_add_f32 v[92:93], v[92:93], v[156:157]
	v_lshl_add_u64 v[100:101], v[96:97], 0, v[192:193]
	v_pk_add_f32 v[90:91], v[90:91], v[154:155]
	v_pk_add_f32 v[88:89], v[88:89], v[152:153]
	global_store_dwordx4 v[204:205], v[92:95], off nt
	global_store_dwordx4 v[204:205], v[88:91], off offset:16 nt
	v_cvt_pk_bf16_f32 v96, v92, v93
	v_mul_f32_e32 v93, v93, v93
	v_fmac_f32_e32 v93, v92, v92
	v_mul_f32_e32 v92, v95, v95
	v_cvt_pk_bf16_f32 v98, v88, v89
	v_fmac_f32_e32 v92, v94, v94
	v_mul_f32_e32 v89, v89, v89
	v_add_f32_e32 v92, v93, v92
	v_fmac_f32_e32 v89, v88, v88
	v_add_f32_e32 v88, v89, v92
	v_mul_f32_e32 v89, v91, v91
	v_fmac_f32_e32 v89, v90, v90
	v_pk_add_f32 v[86:87], v[86:87], v[150:151]
	v_pk_add_f32 v[84:85], v[84:85], v[148:149]
	v_cvt_pk_bf16_f32 v99, v90, v91
	v_add_f32_e32 v88, v89, v88
	v_mul_f32_e32 v89, v85, v85
	v_mul_f32_e32 v90, v87, v87
	v_pk_add_f32 v[80:81], v[80:81], v[144:145]
	v_fmac_f32_e32 v89, v84, v84
	v_fmac_f32_e32 v90, v86, v86
	v_add_f32_e32 v89, v89, v90
	v_mul_f32_e32 v90, v81, v81
	v_pk_add_f32 v[82:83], v[82:83], v[146:147]
	v_fmac_f32_e32 v90, v80, v80
	v_add_f32_e32 v89, v90, v89
	v_mul_f32_e32 v90, v83, v83
	v_fmac_f32_e32 v90, v82, v82
	v_add_f32_e32 v89, v90, v89
	v_add_f32_e32 v88, v88, v89
	ds_bpermute_b32 v89, v218, v88
	v_lshlrev_b64 v[100:101], 1, v[100:101]
	v_cvt_pk_bf16_f32 v97, v94, v95
	v_lshl_add_u64 v[102:103], s[80:81], 0, v[100:101]
	global_store_dwordx4 v[102:103], v[96:99], off
	global_store_dwordx4 v[204:205], v[84:87], off offset:512 nt
	global_store_dwordx4 v[204:205], v[80:83], off offset:528 nt
	v_or_b32_e32 v100, 0x100, v100
	v_cvt_pk_bf16_f32 v84, v84, v85
	v_cvt_pk_bf16_f32 v85, v86, v87
	v_cvt_pk_bf16_f32 v86, v80, v81
	s_waitcnt lgkmcnt(0)
	v_add_f32_e32 v80, v88, v89
	ds_bpermute_b32 v81, v217, v80
	v_cvt_pk_bf16_f32 v87, v82, v83
	v_lshl_add_u64 v[82:83], s[80:81], 0, v[100:101]
	global_store_dwordx4 v[82:83], v[84:87], off
	s_and_saveexec_b64 s[22:23], s[0:1]
	s_cbranch_execz .LBB0_1002
	v_lshl_add_u64 v[82:83], v[202:203], 2, s[8:9]
	s_waitcnt lgkmcnt(0)
	v_add_f32_e32 v80, v80, v81
	global_atomic_add_f32 v[82:83], v80, off
.LBB0_1002:
	s_or_b64 exec, exec, s[22:23]
	s_waitcnt lgkmcnt(0)
	v_lshlrev_b64 v[80:81], 11, v[198:199]
	v_pk_add_f32 v[78:79], v[78:79], v[142:143]
	v_pk_add_f32 v[76:77], v[76:77], v[140:141]
	v_lshl_add_u64 v[84:85], v[80:81], 0, v[192:193]
	v_pk_add_f32 v[74:75], v[74:75], v[138:139]
	v_pk_add_f32 v[72:73], v[72:73], v[136:137]
	global_store_dwordx4 v[200:201], v[76:79], off nt
	global_store_dwordx4 v[200:201], v[72:75], off offset:16 nt
	v_cvt_pk_bf16_f32 v80, v76, v77
	v_mul_f32_e32 v77, v77, v77
	v_fmac_f32_e32 v77, v76, v76
	v_mul_f32_e32 v76, v79, v79
	v_cvt_pk_bf16_f32 v82, v72, v73
	v_fmac_f32_e32 v76, v78, v78
	v_mul_f32_e32 v73, v73, v73
	v_add_f32_e32 v76, v77, v76
	v_fmac_f32_e32 v73, v72, v72
	v_add_f32_e32 v72, v73, v76
	v_mul_f32_e32 v73, v75, v75
	v_fmac_f32_e32 v73, v74, v74
	v_pk_add_f32 v[70:71], v[70:71], v[134:135]
	v_pk_add_f32 v[68:69], v[68:69], v[132:133]
	v_cvt_pk_bf16_f32 v83, v74, v75
	v_add_f32_e32 v72, v73, v72
	v_mul_f32_e32 v73, v69, v69
	v_mul_f32_e32 v74, v71, v71
	v_pk_add_f32 v[64:65], v[64:65], v[128:129]
	v_fmac_f32_e32 v73, v68, v68
	v_fmac_f32_e32 v74, v70, v70
	v_add_f32_e32 v73, v73, v74
	v_mul_f32_e32 v74, v65, v65
	v_pk_add_f32 v[66:67], v[66:67], v[130:131]
	v_fmac_f32_e32 v74, v64, v64
	v_add_f32_e32 v73, v74, v73
	v_mul_f32_e32 v74, v67, v67
	v_fmac_f32_e32 v74, v66, v66
	v_add_f32_e32 v73, v74, v73
	v_add_f32_e32 v72, v72, v73
	ds_bpermute_b32 v73, v218, v72
	v_lshlrev_b64 v[84:85], 1, v[84:85]
	v_cvt_pk_bf16_f32 v81, v78, v79
	v_lshl_add_u64 v[86:87], s[80:81], 0, v[84:85]
	global_store_dwordx4 v[86:87], v[80:83], off
	global_store_dwordx4 v[200:201], v[68:71], off offset:512 nt
	global_store_dwordx4 v[200:201], v[64:67], off offset:528 nt
	v_or_b32_e32 v84, 0x100, v84
	v_cvt_pk_bf16_f32 v68, v68, v69
	v_cvt_pk_bf16_f32 v69, v70, v71
	v_cvt_pk_bf16_f32 v70, v64, v65
	s_waitcnt lgkmcnt(0)
	v_add_f32_e32 v64, v72, v73
	ds_bpermute_b32 v65, v217, v64
	v_cvt_pk_bf16_f32 v71, v66, v67
	v_lshl_add_u64 v[66:67], s[80:81], 0, v[84:85]
	global_store_dwordx4 v[66:67], v[68:71], off
	s_and_saveexec_b64 s[22:23], s[0:1]
	s_cbranch_execz .LBB0_1004
	v_lshl_add_u64 v[66:67], v[198:199], 2, s[8:9]
	s_waitcnt lgkmcnt(0)
	v_add_f32_e32 v64, v64, v65
	global_atomic_add_f32 v[66:67], v64, off
; __device__ __forceinline__ unsigned cvtpk(float lo, float hi) { f32x2_t v = {lo, hi}; bf16x2_t b = __builtin_convertvector(v, bf16x2_t); return __builtin_bit_cast(unsigned, b); }
;     __device__ __forceinline__ void operator()(const pg8::f32x4 (&acc)[2][2][4][2], const pg8::Unit& u, int wr, int wc, int fr, int fq) const {
;     ...
;         for (int ai = 0; ai < 2; ++ai) {
;             pg8::f32x4 rv[4][2][2];
; #pragma unroll
;             for (int m = 0; m < 4; ++m)
; #pragma unroll
;                 for (int bj = 0; bj < 2; ++bj) { const size_t off = (size_t)(row0 + ai * 128 + m * 16) * DM + colb + bj * 128;
;                     rv[m][bj][0] = *(const pg8::f32x4*)(R + off); rv[m][bj][1] = *(const pg8::f32x4*)(R + off + 4); }
; #pragma unroll
;             for (int m = 0; m < 4; ++m) {
;                 const int row = row0 + ai * 128 + m * 16;
;                 float sq = 0.f;
; #pragma unroll
;                 for (int bj = 0; bj < 2; ++bj) {
;                     const size_t off = (size_t)row * DM + colb + bj * 128;
;                     const pg8::f32x4 v0 = rv[m][bj][0] + acc[ai][bj][m][0] * alpha, v1 = rv[m][bj][1] + acc[ai][bj][m][1] * alpha;
;                     *(pg8::f32x4*)(X + off) = v0; *(pg8::f32x4*)(X + off + 4) = v1;
;                     u32x4 w; w[0] = cvtpk(v0[0], v0[1]); w[1] = cvtpk(v0[2], v0[3]); w[2] = cvtpk(v1[0], v1[1]); w[3] = cvtpk(v1[2], v1[3]);
;                     *(u32x4*)(XB + off) = w;
;                     sq += (v0[0] * v0[0] + v0[1] * v0[1]) + (v0[2] * v0[2] + v0[3] * v0[3]) + (v1[0] * v1[0] + v1[1] * v1[1]) + (v1[2] * v1[2] + v1[3] * v1[3]);
;                 }
;                 sq += __shfl_xor(sq, 16); sq += __shfl_xor(sq, 32);
;                 if (fq == 0) atomicAdd(ssout + row, sq);
;             }
.LBB0_1004:
	s_or_b64 exec, exec, s[22:23]
	v_add_u32_e32 v124, 0x80, v194
	v_ashrrev_i32_e32 v125, 31, v124
	s_waitcnt lgkmcnt(0)
	v_lshlrev_b64 v[64:65], 13, v[124:125]
	v_lshl_add_u64 v[142:143], v[196:197], 0, v[64:65]
	global_load_dwordx4 v[126:129], v[142:143], off
	global_load_dwordx4 v[130:133], v[142:143], off offset:16
	global_load_dwordx4 v[134:137], v[142:143], off offset:512
	global_load_dwordx4 v[138:141], v[142:143], off offset:528
	v_add_u32_e32 v120, 0x90, v194
	v_add_u32_e32 v116, 0xa0, v194
	v_add_u32_e32 v112, 0xb0, v194
	v_ashrrev_i32_e32 v121, 31, v120
	v_ashrrev_i32_e32 v117, 31, v116
	v_ashrrev_i32_e32 v113, 31, v112
	v_lshlrev_b64 v[64:65], 13, v[120:121]
	v_lshlrev_b64 v[66:67], 13, v[116:117]
	v_lshlrev_b64 v[68:69], 13, v[112:113]
	v_lshl_add_u64 v[122:123], v[196:197], 0, v[64:65]
	v_lshl_add_u64 v[118:119], v[196:197], 0, v[66:67]
	v_lshl_add_u64 v[114:115], v[196:197], 0, v[68:69]
	global_load_dwordx4 v[104:107], v[122:123], off offset:16
	global_load_dwordx4 v[108:111], v[122:123], off
	global_load_dwordx4 v[96:99], v[122:123], off offset:528
	global_load_dwordx4 v[100:103], v[122:123], off offset:512
	global_load_dwordx4 v[88:91], v[118:119], off offset:16
	global_load_dwordx4 v[92:95], v[118:119], off
	global_load_dwordx4 v[80:83], v[118:119], off offset:528
	global_load_dwordx4 v[84:87], v[118:119], off offset:512
	global_load_dwordx4 v[72:75], v[114:115], off offset:16
	global_load_dwordx4 v[76:79], v[114:115], off
	global_load_dwordx4 v[64:67], v[114:115], off offset:528
	global_load_dwordx4 v[68:71], v[114:115], off offset:512
	v_lshlrev_b64 v[144:145], 11, v[124:125]
	v_lshl_add_u64 v[144:145], v[144:145], 0, v[192:193]
	v_lshlrev_b64 v[144:145], 1, v[144:145]
	v_lshl_add_u64 v[146:147], s[80:81], 0, v[144:145]
	v_or_b32_e32 v144, 0x100, v144
	s_waitcnt vmcnt(15)
	v_pk_add_f32 v[62:63], v[62:63], v[128:129]
	v_pk_add_f32 v[60:61], v[60:61], v[126:127]
	s_waitcnt vmcnt(13)
	v_pk_add_f32 v[54:55], v[54:55], v[136:137]
	v_pk_add_f32 v[52:53], v[52:53], v[134:135]
	v_pk_add_f32 v[58:59], v[58:59], v[132:133]
	v_pk_add_f32 v[56:57], v[56:57], v[130:131]
	s_waitcnt vmcnt(12)
	v_pk_add_f32 v[48:49], v[48:49], v[138:139]
	global_store_dwordx4 v[142:143], v[60:63], off nt
	global_store_dwordx4 v[142:143], v[56:59], off offset:16 nt
	v_cvt_pk_bf16_f32 v126, v60, v61
	v_cvt_pk_bf16_f32 v127, v62, v63
	v_mul_f32_e32 v61, v61, v61
	v_mul_f32_e32 v63, v63, v63
	v_mul_f32_e32 v130, v53, v53
	v_mul_f32_e32 v131, v55, v55
	v_pk_add_f32 v[50:51], v[50:51], v[140:141]
	v_cvt_pk_bf16_f32 v128, v56, v57
	v_cvt_pk_bf16_f32 v129, v58, v59
	v_mul_f32_e32 v57, v57, v57
	v_mul_f32_e32 v59, v59, v59
	v_mul_f32_e32 v132, v49, v49
	v_fmac_f32_e32 v61, v60, v60
	v_fmac_f32_e32 v63, v62, v62
	v_fmac_f32_e32 v130, v52, v52
	v_fmac_f32_e32 v131, v54, v54
	v_mul_f32_e32 v133, v51, v51
	v_fmac_f32_e32 v57, v56, v56
	v_fmac_f32_e32 v59, v58, v58
	v_fmac_f32_e32 v132, v48, v48
	v_add_f32_e32 v56, v61, v63
	v_add_f32_e32 v58, v130, v131
	v_fmac_f32_e32 v133, v50, v50
	v_add_f32_e32 v56, v57, v56
	v_add_f32_e32 v57, v132, v58
	v_add_f32_e32 v56, v59, v56
	v_add_f32_e32 v57, v133, v57
	v_add_f32_e32 v56, v56, v57
	ds_bpermute_b32 v57, v218, v56
	global_store_dwordx4 v[146:147], v[126:129], off
	global_store_dwordx4 v[142:143], v[52:55], off offset:512 nt
	global_store_dwordx4 v[142:143], v[48:51], off offset:528 nt
	s_nop 0
	v_cvt_pk_bf16_f32 v52, v52, v53
	v_cvt_pk_bf16_f32 v53, v54, v55
	v_cvt_pk_bf16_f32 v54, v48, v49
	s_waitcnt lgkmcnt(0)
	v_add_f32_e32 v48, v56, v57
	ds_bpermute_b32 v49, v217, v48
	v_cvt_pk_bf16_f32 v55, v50, v51
	v_lshl_add_u64 v[50:51], s[80:81], 0, v[144:145]
	global_store_dwordx4 v[50:51], v[52:55], off
	s_and_saveexec_b64 s[22:23], s[0:1]
	s_cbranch_execz .LBB0_1006
	v_lshl_add_u64 v[50:51], v[124:125], 2, s[8:9]
	s_waitcnt lgkmcnt(0)
	v_add_f32_e32 v48, v48, v49
	global_atomic_add_f32 v[50:51], v48, off
.LBB0_1006:
	s_or_b64 exec, exec, s[22:23]
	s_waitcnt lgkmcnt(0)
	v_lshlrev_b64 v[48:49], 11, v[120:121]
	s_waitcnt vmcnt(16)
	v_pk_add_f32 v[46:47], v[46:47], v[110:111]
	v_pk_add_f32 v[44:45], v[44:45], v[108:109]
	v_lshl_add_u64 v[52:53], v[48:49], 0, v[192:193]
	v_pk_add_f32 v[42:43], v[42:43], v[106:107]
	v_pk_add_f32 v[40:41], v[40:41], v[104:105]
	global_store_dwordx4 v[122:123], v[44:47], off nt
	global_store_dwordx4 v[122:123], v[40:43], off offset:16 nt
	v_cvt_pk_bf16_f32 v48, v44, v45
	v_mul_f32_e32 v45, v45, v45
	v_fmac_f32_e32 v45, v44, v44
	v_mul_f32_e32 v44, v47, v47
	v_cvt_pk_bf16_f32 v50, v40, v41
	v_fmac_f32_e32 v44, v46, v46
	v_mul_f32_e32 v41, v41, v41
	v_add_f32_e32 v44, v45, v44
	v_fmac_f32_e32 v41, v40, v40
	v_add_f32_e32 v40, v41, v44
	v_mul_f32_e32 v41, v43, v43
	v_fmac_f32_e32 v41, v42, v42
	s_waitcnt vmcnt(16)
	v_pk_add_f32 v[38:39], v[38:39], v[102:103]
	v_pk_add_f32 v[36:37], v[36:37], v[100:101]
	v_cvt_pk_bf16_f32 v51, v42, v43
	v_add_f32_e32 v40, v41, v40
	v_mul_f32_e32 v41, v37, v37
	v_mul_f32_e32 v42, v39, v39
	v_pk_add_f32 v[32:33], v[32:33], v[96:97]
	v_fmac_f32_e32 v41, v36, v36
	v_fmac_f32_e32 v42, v38, v38
	v_add_f32_e32 v41, v41, v42
	v_mul_f32_e32 v42, v33, v33
	v_pk_add_f32 v[34:35], v[34:35], v[98:99]
	v_fmac_f32_e32 v42, v32, v32
	v_add_f32_e32 v41, v42, v41
	v_mul_f32_e32 v42, v35, v35
	v_fmac_f32_e32 v42, v34, v34
	v_add_f32_e32 v41, v42, v41
	v_add_f32_e32 v40, v40, v41
	ds_bpermute_b32 v41, v218, v40
	v_lshlrev_b64 v[52:53], 1, v[52:53]
	v_cvt_pk_bf16_f32 v49, v46, v47
	v_lshl_add_u64 v[54:55], s[80:81], 0, v[52:53]
	global_store_dwordx4 v[54:55], v[48:51], off
	global_store_dwordx4 v[122:123], v[36:39], off offset:512 nt
	global_store_dwordx4 v[122:123], v[32:35], off offset:528 nt
	v_or_b32_e32 v52, 0x100, v52
	v_cvt_pk_bf16_f32 v36, v36, v37
	v_cvt_pk_bf16_f32 v37, v38, v39
	v_cvt_pk_bf16_f32 v38, v32, v33
	s_waitcnt lgkmcnt(0)
	v_add_f32_e32 v32, v40, v41
	ds_bpermute_b32 v33, v217, v32
	v_cvt_pk_bf16_f32 v39, v34, v35
	v_lshl_add_u64 v[34:35], s[80:81], 0, v[52:53]
	global_store_dwordx4 v[34:35], v[36:39], off
	s_and_saveexec_b64 s[22:23], s[0:1]
	s_cbranch_execz .LBB0_1008
	v_lshl_add_u64 v[34:35], v[120:121], 2, s[8:9]
	s_waitcnt lgkmcnt(0)
	v_add_f32_e32 v32, v32, v33
	global_atomic_add_f32 v[34:35], v32, off
; __device__ __forceinline__ unsigned cvtpk(float lo, float hi) { f32x2_t v = {lo, hi}; bf16x2_t b = __builtin_convertvector(v, bf16x2_t); return __builtin_bit_cast(unsigned, b); }
;     __device__ __forceinline__ void operator()(const pg8::f32x4 (&acc)[2][2][4][2], const pg8::Unit& u, int wr, int wc, int fr, int fq) const {
;     ...
;             for (int m = 0; m < 4; ++m) {
;                 const int row = row0 + ai * 128 + m * 16;
;                 float sq = 0.f;
; #pragma unroll
;                 for (int bj = 0; bj < 2; ++bj) {
;                     const size_t off = (size_t)row * DM + colb + bj * 128;
;                     const pg8::f32x4 v0 = rv[m][bj][0] + acc[ai][bj][m][0] * alpha, v1 = rv[m][bj][1] + acc[ai][bj][m][1] * alpha;
;                     *(pg8::f32x4*)(X + off) = v0; *(pg8::f32x4*)(X + off + 4) = v1;
;                     u32x4 w; w[0] = cvtpk(v0[0], v0[1]); w[1] = cvtpk(v0[2], v0[3]); w[2] = cvtpk(v1[0], v1[1]); w[3] = cvtpk(v1[2], v1[3]);
;                     *(u32x4*)(XB + off) = w;
;                     sq += (v0[0] * v0[0] + v0[1] * v0[1]) + (v0[2] * v0[2] + v0[3] * v0[3]) + (v1[0] * v1[0] + v1[1] * v1[1]) + (v1[2] * v1[2] + v1[3] * v1[3]);
;                 }
;                 sq += __shfl_xor(sq, 16); sq += __shfl_xor(sq, 32);
;                 if (fq == 0) atomicAdd(ssout + row, sq);
;             }
.LBB0_1008:
	s_or_b64 exec, exec, s[22:23]
	s_waitcnt lgkmcnt(0)
	v_lshlrev_b64 v[32:33], 11, v[116:117]
	s_waitcnt vmcnt(18)
	v_pk_add_f32 v[30:31], v[30:31], v[94:95]
	v_pk_add_f32 v[28:29], v[28:29], v[92:93]
	v_lshl_add_u64 v[36:37], v[32:33], 0, v[192:193]
	v_pk_add_f32 v[26:27], v[26:27], v[90:91]
	v_pk_add_f32 v[24:25], v[24:25], v[88:89]
	global_store_dwordx4 v[118:119], v[28:31], off nt
	global_store_dwordx4 v[118:119], v[24:27], off offset:16 nt
	v_cvt_pk_bf16_f32 v32, v28, v29
	v_mul_f32_e32 v29, v29, v29
	v_fmac_f32_e32 v29, v28, v28
	v_mul_f32_e32 v28, v31, v31
	v_cvt_pk_bf16_f32 v34, v24, v25
	v_fmac_f32_e32 v28, v30, v30
	v_mul_f32_e32 v25, v25, v25
	v_add_f32_e32 v28, v29, v28
	v_fmac_f32_e32 v25, v24, v24
	v_add_f32_e32 v24, v25, v28
	v_mul_f32_e32 v25, v27, v27
	v_fmac_f32_e32 v25, v26, v26
	s_waitcnt vmcnt(18)
	v_pk_add_f32 v[22:23], v[22:23], v[86:87]
	v_pk_add_f32 v[20:21], v[20:21], v[84:85]
	v_cvt_pk_bf16_f32 v35, v26, v27
	v_add_f32_e32 v24, v25, v24
	v_mul_f32_e32 v25, v21, v21
	v_mul_f32_e32 v26, v23, v23
	v_pk_add_f32 v[16:17], v[16:17], v[80:81]
	v_fmac_f32_e32 v25, v20, v20
	v_fmac_f32_e32 v26, v22, v22
	v_add_f32_e32 v25, v25, v26
	v_mul_f32_e32 v26, v17, v17
	v_pk_add_f32 v[18:19], v[18:19], v[82:83]
	v_fmac_f32_e32 v26, v16, v16
	v_add_f32_e32 v25, v26, v25
	v_mul_f32_e32 v26, v19, v19
	v_fmac_f32_e32 v26, v18, v18
	v_add_f32_e32 v25, v26, v25
	v_add_f32_e32 v24, v24, v25
	ds_bpermute_b32 v25, v218, v24
	v_lshlrev_b64 v[36:37], 1, v[36:37]
	v_cvt_pk_bf16_f32 v33, v30, v31
	v_lshl_add_u64 v[38:39], s[80:81], 0, v[36:37]
	global_store_dwordx4 v[38:39], v[32:35], off
	global_store_dwordx4 v[118:119], v[20:23], off offset:512 nt
	global_store_dwordx4 v[118:119], v[16:19], off offset:528 nt
	v_or_b32_e32 v36, 0x100, v36
	v_cvt_pk_bf16_f32 v20, v20, v21
	v_cvt_pk_bf16_f32 v21, v22, v23
	v_cvt_pk_bf16_f32 v22, v16, v17
	s_waitcnt lgkmcnt(0)
	v_add_f32_e32 v16, v24, v25
	ds_bpermute_b32 v17, v217, v16
	v_cvt_pk_bf16_f32 v23, v18, v19
	v_lshl_add_u64 v[18:19], s[80:81], 0, v[36:37]
	global_store_dwordx4 v[18:19], v[20:23], off
	s_and_saveexec_b64 s[22:23], s[0:1]
	s_cbranch_execz .LBB0_1010
	v_lshl_add_u64 v[18:19], v[116:117], 2, s[8:9]
	s_waitcnt lgkmcnt(0)
	v_add_f32_e32 v16, v16, v17
	global_atomic_add_f32 v[18:19], v16, off
.LBB0_1010:
	s_or_b64 exec, exec, s[22:23]
	s_waitcnt lgkmcnt(0)
	v_lshlrev_b64 v[16:17], 11, v[112:113]
	s_waitcnt vmcnt(20)
	v_pk_add_f32 v[14:15], v[14:15], v[78:79]
	v_pk_add_f32 v[12:13], v[12:13], v[76:77]
	v_lshl_add_u64 v[20:21], v[16:17], 0, v[192:193]
	v_pk_add_f32 v[10:11], v[10:11], v[74:75]
	v_pk_add_f32 v[8:9], v[8:9], v[72:73]
	global_store_dwordx4 v[114:115], v[12:15], off nt
	global_store_dwordx4 v[114:115], v[8:11], off offset:16 nt
	v_cvt_pk_bf16_f32 v16, v12, v13
	v_mul_f32_e32 v13, v13, v13
	v_fmac_f32_e32 v13, v12, v12
	v_mul_f32_e32 v12, v15, v15
	v_cvt_pk_bf16_f32 v18, v8, v9
	v_fmac_f32_e32 v12, v14, v14
	v_mul_f32_e32 v9, v9, v9
	v_add_f32_e32 v12, v13, v12
	v_fmac_f32_e32 v9, v8, v8
	v_add_f32_e32 v8, v9, v12
	v_mul_f32_e32 v9, v11, v11
	v_fmac_f32_e32 v9, v10, v10
	s_waitcnt vmcnt(20)
	v_pk_add_f32 v[6:7], v[6:7], v[70:71]
	v_pk_add_f32 v[4:5], v[4:5], v[68:69]
	v_cvt_pk_bf16_f32 v19, v10, v11
	v_add_f32_e32 v8, v9, v8
	v_mul_f32_e32 v9, v5, v5
	v_mul_f32_e32 v10, v7, v7
	v_pk_add_f32 v[0:1], v[0:1], v[64:65]
	v_fmac_f32_e32 v9, v4, v4
	v_fmac_f32_e32 v10, v6, v6
	v_add_f32_e32 v9, v9, v10
	v_mul_f32_e32 v10, v1, v1
	v_pk_add_f32 v[2:3], v[2:3], v[66:67]
	v_fmac_f32_e32 v10, v0, v0
	v_add_f32_e32 v9, v10, v9
	v_mul_f32_e32 v10, v3, v3
	v_fmac_f32_e32 v10, v2, v2
	v_add_f32_e32 v9, v10, v9
	v_add_f32_e32 v8, v8, v9
	ds_bpermute_b32 v9, v218, v8
	v_lshlrev_b64 v[20:21], 1, v[20:21]
	v_cvt_pk_bf16_f32 v17, v14, v15
	v_lshl_add_u64 v[22:23], s[80:81], 0, v[20:21]
	global_store_dwordx4 v[22:23], v[16:19], off
	global_store_dwordx4 v[114:115], v[4:7], off offset:512 nt
	global_store_dwordx4 v[114:115], v[0:3], off offset:528 nt
	v_or_b32_e32 v20, 0x100, v20
	v_cvt_pk_bf16_f32 v4, v4, v5
	v_cvt_pk_bf16_f32 v5, v6, v7
	v_cvt_pk_bf16_f32 v6, v0, v1
	s_waitcnt lgkmcnt(0)
	v_add_f32_e32 v0, v8, v9
	ds_bpermute_b32 v1, v217, v0
	v_cvt_pk_bf16_f32 v7, v2, v3
	v_lshl_add_u64 v[2:3], s[80:81], 0, v[20:21]
	global_store_dwordx4 v[2:3], v[4:7], off
	s_and_saveexec_b64 s[22:23], s[0:1]
	s_cbranch_execz .LBB0_1012
	v_lshl_add_u64 v[2:3], v[112:113], 2, s[8:9]
	s_waitcnt lgkmcnt(0)
	v_add_f32_e32 v0, v0, v1
	global_atomic_add_f32 v[2:3], v0, off

; __device__ __forceinline__ unsigned cvtpk(float lo, float hi) { f32x2_t v = {lo, hi}; bf16x2_t b = __builtin_convertvector(v, bf16x2_t); return __builtin_bit_cast(unsigned, b); }
;     __device__ __forceinline__ void operator()(const pg8::f32x4 (&acc)[2][2][4][2], const pg8::Unit& u, int wr, int wc, int fr, int fq) const {
;         const int row0 = u.pm * 256 + wr * 64 + fr, colb = u.pn * 256 + wc * 32 + 8 * fq;
; #pragma unroll
;         for (int ai = 0; ai < 2; ++ai) {
;             pg8::f32x4 rv[4][2][2];
; #pragma unroll
;             for (int m = 0; m < 4; ++m)
; #pragma unroll
;                 for (int bj = 0; bj < 2; ++bj) { const size_t off = (size_t)(row0 + ai * 128 + m * 16) * DM + colb + bj * 128;
;                     rv[m][bj][0] = *(const pg8::f32x4*)(R + off); rv[m][bj][1] = *(const pg8::f32x4*)(R + off + 4); }
; #pragma unroll
;             for (int m = 0; m < 4; ++m) {
;                 const int row = row0 + ai * 128 + m * 16;
;                 float sq = 0.f;
; #pragma unroll
;                 for (int bj = 0; bj < 2; ++bj) {
;                     const size_t off = (size_t)row * DM + colb + bj * 128;
;                     const pg8::f32x4 v0 = rv[m][bj][0] + acc[ai][bj][m][0] * alpha, v1 = rv[m][bj][1] + acc[ai][bj][m][1] * alpha;
;                     *(pg8::f32x4*)(X + off) = v0; *(pg8::f32x4*)(X + off + 4) = v1;
;                     u32x4 w; w[0] = cvtpk(v0[0], v0[1]); w[1] = cvtpk(v0[2], v0[3]); w[2] = cvtpk(v1[0], v1[1]); w[3] = cvtpk(v1[2], v1[3]);
;                     *(u32x4*)(XB + off) = w;
;                     sq += (v0[0] * v0[0] + v0[1] * v0[1]) + (v0[2] * v0[2] + v0[3] * v0[3]) + (v1[0] * v1[0] + v1[1] * v1[1]) + (v1[2] * v1[2] + v1[3] * v1[3]);
;                 }
;                 sq += __shfl_xor(sq, 16); sq += __shfl_xor(sq, 32);
;                 if (fq == 0) atomicAdd(ssout + row, sq);
;             }
.LBB0_1207:
	v_lshl_add_u32 v194, s42, 8, v210
	v_lshl_or_b32 v192, s43, 8, v212
	v_ashrrev_i32_e32 v193, 31, v192
	v_ashrrev_i32_e32 v195, 31, v194
	v_lshl_add_u64 v[196:197], v[192:193], 2, s[62:63]
	v_lshlrev_b64 v[128:129], 13, v[194:195]
	v_lshl_add_u64 v[238:239], v[196:197], 0, v[128:129]
	global_load_dwordx4 v[222:225], v[238:239], off
	global_load_dwordx4 v[226:229], v[238:239], off offset:16
	global_load_dwordx4 v[230:233], v[238:239], off offset:512
	global_load_dwordx4 v[234:237], v[238:239], off offset:528
	v_or_b32_e32 v206, 16, v194
	v_or_b32_e32 v202, 32, v194
	v_or_b32_e32 v198, 48, v194
	v_ashrrev_i32_e32 v207, 31, v206
	v_ashrrev_i32_e32 v203, 31, v202
	v_ashrrev_i32_e32 v199, 31, v198
	v_lshlrev_b64 v[128:129], 13, v[206:207]
	v_lshlrev_b64 v[130:131], 13, v[202:203]
	v_lshlrev_b64 v[132:133], 13, v[198:199]
	v_lshl_add_u64 v[208:209], v[196:197], 0, v[128:129]
	v_lshl_add_u64 v[204:205], v[196:197], 0, v[130:131]
	v_lshl_add_u64 v[200:201], v[196:197], 0, v[132:133]
	global_load_dwordx4 v[168:171], v[208:209], off offset:16
	global_load_dwordx4 v[172:175], v[208:209], off
	global_load_dwordx4 v[160:163], v[208:209], off offset:528
	global_load_dwordx4 v[164:167], v[208:209], off offset:512
	global_load_dwordx4 v[152:155], v[204:205], off offset:16
	global_load_dwordx4 v[156:159], v[204:205], off
	global_load_dwordx4 v[144:147], v[204:205], off offset:528
	global_load_dwordx4 v[148:151], v[204:205], off offset:512
	global_load_dwordx4 v[136:139], v[200:201], off offset:16
	global_load_dwordx4 v[140:143], v[200:201], off
	global_load_dwordx4 v[128:131], v[200:201], off offset:528
	global_load_dwordx4 v[132:135], v[200:201], off offset:512
	v_and_b32_e32 v218, 64, v216
	v_xor_b32_e32 v217, 16, v216
	v_add_u32_e32 v218, 64, v218
	v_xor_b32_e32 v219, 32, v216
	v_cmp_lt_i32_e32 vcc, v217, v218
	v_lshlrev_b64 v[240:241], 11, v[194:195]
	v_lshl_add_u64 v[240:241], v[240:241], 0, v[192:193]
	v_cndmask_b32_e32 v217, v216, v217, vcc
	v_cmp_lt_i32_e32 vcc, v219, v218
	v_lshlrev_b32_e32 v218, 2, v217
	v_lshlrev_b64 v[240:241], 1, v[240:241]
	v_cndmask_b32_e32 v219, v216, v219, vcc
	v_lshlrev_b32_e32 v217, 2, v219
	v_lshl_add_u64 v[242:243], s[80:81], 0, v[240:241]
	v_or_b32_e32 v240, 0x100, v240
	s_waitcnt vmcnt(0)
	v_pk_fma_f32 v[126:127], v[126:127], 0.5, v[224:225] op_sel_hi:[1,0,1]
	v_pk_fma_f32 v[124:125], v[124:125], 0.5, v[222:223] op_sel_hi:[1,0,1]
	v_pk_fma_f32 v[118:119], v[118:119], 0.5, v[232:233] op_sel_hi:[1,0,1]
	v_pk_fma_f32 v[116:117], v[116:117], 0.5, v[230:231] op_sel_hi:[1,0,1]
	v_pk_fma_f32 v[122:123], v[122:123], 0.5, v[228:229] op_sel_hi:[1,0,1]
	v_pk_fma_f32 v[120:121], v[120:121], 0.5, v[226:227] op_sel_hi:[1,0,1]
	v_pk_fma_f32 v[112:113], v[112:113], 0.5, v[234:235] op_sel_hi:[1,0,1]
	global_store_dwordx4 v[238:239], v[124:127], off nt
	global_store_dwordx4 v[238:239], v[120:123], off offset:16 nt
	v_cvt_pk_bf16_f32 v222, v124, v125
	v_cvt_pk_bf16_f32 v223, v126, v127
	v_mul_f32_e32 v125, v125, v125
	v_mul_f32_e32 v127, v127, v127
	v_mul_f32_e32 v219, v117, v117
	v_mul_f32_e32 v221, v119, v119
	v_pk_fma_f32 v[114:115], v[114:115], 0.5, v[236:237] op_sel_hi:[1,0,1]
	v_cvt_pk_bf16_f32 v224, v120, v121
	v_cvt_pk_bf16_f32 v225, v122, v123
	v_mul_f32_e32 v121, v121, v121
	v_mul_f32_e32 v123, v123, v123
	v_mul_f32_e32 v226, v113, v113
	v_fmac_f32_e32 v125, v124, v124
	v_fmac_f32_e32 v127, v126, v126
	v_fmac_f32_e32 v219, v116, v116
	v_fmac_f32_e32 v221, v118, v118
	v_mul_f32_e32 v227, v115, v115
	v_fmac_f32_e32 v121, v120, v120
	v_fmac_f32_e32 v123, v122, v122
	v_fmac_f32_e32 v226, v112, v112
	v_add_f32_e32 v120, v125, v127
	v_add_f32_e32 v122, v219, v221
	v_fmac_f32_e32 v227, v114, v114
	v_add_f32_e32 v120, v121, v120
	v_add_f32_e32 v121, v226, v122
	v_add_f32_e32 v120, v123, v120
	v_add_f32_e32 v121, v227, v121
	v_add_f32_e32 v120, v120, v121
	ds_bpermute_b32 v121, v218, v120
	global_store_dwordx4 v[242:243], v[222:225], off
	global_store_dwordx4 v[238:239], v[116:119], off offset:512 nt
	global_store_dwordx4 v[238:239], v[112:115], off offset:528 nt
	s_nop 0
	v_cvt_pk_bf16_f32 v116, v116, v117
	v_cvt_pk_bf16_f32 v117, v118, v119
	v_cvt_pk_bf16_f32 v118, v112, v113
	s_waitcnt lgkmcnt(0)
	v_add_f32_e32 v112, v120, v121
	ds_bpermute_b32 v113, v217, v112
	v_cvt_pk_bf16_f32 v119, v114, v115
	v_lshl_add_u64 v[114:115], s[80:81], 0, v[240:241]
	global_store_dwordx4 v[114:115], v[116:119], off
	s_and_saveexec_b64 s[20:21], s[0:1]
	s_cbranch_execz .LBB0_1209
	v_lshl_add_u64 v[114:115], v[194:195], 2, s[12:13]
	s_waitcnt lgkmcnt(0)
	v_add_f32_e32 v112, v112, v113
	global_atomic_add_f32 v[114:115], v112, off
; __device__ __forceinline__ unsigned cvtpk(float lo, float hi) { f32x2_t v = {lo, hi}; bf16x2_t b = __builtin_convertvector(v, bf16x2_t); return __builtin_bit_cast(unsigned, b); }
;     __device__ __forceinline__ void operator()(const pg8::f32x4 (&acc)[2][2][4][2], const pg8::Unit& u, int wr, int wc, int fr, int fq) const {
;     ...
;             for (int m = 0; m < 4; ++m) {
;                 const int row = row0 + ai * 128 + m * 16;
;                 float sq = 0.f;
; #pragma unroll
;                 for (int bj = 0; bj < 2; ++bj) {
;                     const size_t off = (size_t)row * DM + colb + bj * 128;
;                     const pg8::f32x4 v0 = rv[m][bj][0] + acc[ai][bj][m][0] * alpha, v1 = rv[m][bj][1] + acc[ai][bj][m][1] * alpha;
;                     *(pg8::f32x4*)(X + off) = v0; *(pg8::f32x4*)(X + off + 4) = v1;
;                     u32x4 w; w[0] = cvtpk(v0[0], v0[1]); w[1] = cvtpk(v0[2], v0[3]); w[2] = cvtpk(v1[0], v1[1]); w[3] = cvtpk(v1[2], v1[3]);
;                     *(u32x4*)(XB + off) = w;
;                     sq += (v0[0] * v0[0] + v0[1] * v0[1]) + (v0[2] * v0[2] + v0[3] * v0[3]) + (v1[0] * v1[0] + v1[1] * v1[1]) + (v1[2] * v1[2] + v1[3] * v1[3]);
;                 }
;                 sq += __shfl_xor(sq, 16); sq += __shfl_xor(sq, 32);
;                 if (fq == 0) atomicAdd(ssout + row, sq);
;             }
.LBB0_1209:
	s_or_b64 exec, exec, s[20:21]
	s_waitcnt lgkmcnt(0)
	v_lshlrev_b64 v[112:113], 11, v[206:207]
	v_pk_fma_f32 v[110:111], v[110:111], 0.5, v[174:175] op_sel_hi:[1,0,1]
	v_pk_fma_f32 v[108:109], v[108:109], 0.5, v[172:173] op_sel_hi:[1,0,1]
	v_lshl_add_u64 v[116:117], v[112:113], 0, v[192:193]
	v_pk_fma_f32 v[106:107], v[106:107], 0.5, v[170:171] op_sel_hi:[1,0,1]
	v_pk_fma_f32 v[104:105], v[104:105], 0.5, v[168:169] op_sel_hi:[1,0,1]
	global_store_dwordx4 v[208:209], v[108:111], off nt
	global_store_dwordx4 v[208:209], v[104:107], off offset:16 nt
	v_cvt_pk_bf16_f32 v112, v108, v109
	v_mul_f32_e32 v109, v109, v109
	v_fmac_f32_e32 v109, v108, v108
	v_mul_f32_e32 v108, v111, v111
	v_cvt_pk_bf16_f32 v114, v104, v105
	v_fmac_f32_e32 v108, v110, v110
	v_mul_f32_e32 v105, v105, v105
	v_add_f32_e32 v108, v109, v108
	v_fmac_f32_e32 v105, v104, v104
	v_add_f32_e32 v104, v105, v108
	v_mul_f32_e32 v105, v107, v107
	v_fmac_f32_e32 v105, v106, v106
	v_pk_fma_f32 v[102:103], v[102:103], 0.5, v[166:167] op_sel_hi:[1,0,1]
	v_pk_fma_f32 v[100:101], v[100:101], 0.5, v[164:165] op_sel_hi:[1,0,1]
	v_cvt_pk_bf16_f32 v115, v106, v107
	v_add_f32_e32 v104, v105, v104
	v_mul_f32_e32 v105, v101, v101
	v_mul_f32_e32 v106, v103, v103
	v_pk_fma_f32 v[96:97], v[96:97], 0.5, v[160:161] op_sel_hi:[1,0,1]
	v_fmac_f32_e32 v105, v100, v100
	v_fmac_f32_e32 v106, v102, v102
	v_add_f32_e32 v105, v105, v106
	v_mul_f32_e32 v106, v97, v97
	v_pk_fma_f32 v[98:99], v[98:99], 0.5, v[162:163] op_sel_hi:[1,0,1]
	v_fmac_f32_e32 v106, v96, v96
	v_add_f32_e32 v105, v106, v105
	v_mul_f32_e32 v106, v99, v99
	v_fmac_f32_e32 v106, v98, v98
	v_add_f32_e32 v105, v106, v105
	v_add_f32_e32 v104, v104, v105
	ds_bpermute_b32 v105, v218, v104
	v_lshlrev_b64 v[116:117], 1, v[116:117]
	v_cvt_pk_bf16_f32 v113, v110, v111
	v_lshl_add_u64 v[118:119], s[80:81], 0, v[116:117]
	global_store_dwordx4 v[118:119], v[112:115], off
	global_store_dwordx4 v[208:209], v[100:103], off offset:512 nt
	global_store_dwordx4 v[208:209], v[96:99], off offset:528 nt
	v_or_b32_e32 v116, 0x100, v116
	v_cvt_pk_bf16_f32 v100, v100, v101
	v_cvt_pk_bf16_f32 v101, v102, v103
	v_cvt_pk_bf16_f32 v102, v96, v97
	s_waitcnt lgkmcnt(0)
	v_add_f32_e32 v96, v104, v105
	ds_bpermute_b32 v97, v217, v96
	v_cvt_pk_bf16_f32 v103, v98, v99
	v_lshl_add_u64 v[98:99], s[80:81], 0, v[116:117]
	global_store_dwordx4 v[98:99], v[100:103], off
	s_and_saveexec_b64 s[20:21], s[0:1]
	s_cbranch_execz .LBB0_1211
	v_lshl_add_u64 v[98:99], v[206:207], 2, s[12:13]
	s_waitcnt lgkmcnt(0)
	v_add_f32_e32 v96, v96, v97
	global_atomic_add_f32 v[98:99], v96, off
.LBB0_1211:
	s_or_b64 exec, exec, s[20:21]
	s_waitcnt lgkmcnt(0)
	v_lshlrev_b64 v[96:97], 11, v[202:203]
	v_pk_fma_f32 v[94:95], v[94:95], 0.5, v[158:159] op_sel_hi:[1,0,1]
	v_pk_fma_f32 v[92:93], v[92:93], 0.5, v[156:157] op_sel_hi:[1,0,1]
	v_lshl_add_u64 v[100:101], v[96:97], 0, v[192:193]
	v_pk_fma_f32 v[90:91], v[90:91], 0.5, v[154:155] op_sel_hi:[1,0,1]
	v_pk_fma_f32 v[88:89], v[88:89], 0.5, v[152:153] op_sel_hi:[1,0,1]
	global_store_dwordx4 v[204:205], v[92:95], off nt
	global_store_dwordx4 v[204:205], v[88:91], off offset:16 nt
	v_cvt_pk_bf16_f32 v96, v92, v93
	v_mul_f32_e32 v93, v93, v93
	v_fmac_f32_e32 v93, v92, v92
	v_mul_f32_e32 v92, v95, v95
	v_cvt_pk_bf16_f32 v98, v88, v89
	v_fmac_f32_e32 v92, v94, v94
	v_mul_f32_e32 v89, v89, v89
	v_add_f32_e32 v92, v93, v92
	v_fmac_f32_e32 v89, v88, v88
	v_add_f32_e32 v88, v89, v92
	v_mul_f32_e32 v89, v91, v91
	v_fmac_f32_e32 v89, v90, v90
	v_pk_fma_f32 v[86:87], v[86:87], 0.5, v[150:151] op_sel_hi:[1,0,1]
	v_pk_fma_f32 v[84:85], v[84:85], 0.5, v[148:149] op_sel_hi:[1,0,1]
	v_cvt_pk_bf16_f32 v99, v90, v91
	v_add_f32_e32 v88, v89, v88
	v_mul_f32_e32 v89, v85, v85
	v_mul_f32_e32 v90, v87, v87
	v_pk_fma_f32 v[80:81], v[80:81], 0.5, v[144:145] op_sel_hi:[1,0,1]
	v_fmac_f32_e32 v89, v84, v84
	v_fmac_f32_e32 v90, v86, v86
	v_add_f32_e32 v89, v89, v90
	v_mul_f32_e32 v90, v81, v81
	v_pk_fma_f32 v[82:83], v[82:83], 0.5, v[146:147] op_sel_hi:[1,0,1]
	v_fmac_f32_e32 v90, v80, v80
	v_add_f32_e32 v89, v90, v89
	v_mul_f32_e32 v90, v83, v83
	v_fmac_f32_e32 v90, v82, v82
	v_add_f32_e32 v89, v90, v89
	v_add_f32_e32 v88, v88, v89
	ds_bpermute_b32 v89, v218, v88
	v_lshlrev_b64 v[100:101], 1, v[100:101]
	v_cvt_pk_bf16_f32 v97, v94, v95
	v_lshl_add_u64 v[102:103], s[80:81], 0, v[100:101]
	global_store_dwordx4 v[102:103], v[96:99], off
	global_store_dwordx4 v[204:205], v[84:87], off offset:512 nt
	global_store_dwordx4 v[204:205], v[80:83], off offset:528 nt
	v_or_b32_e32 v100, 0x100, v100
	v_cvt_pk_bf16_f32 v84, v84, v85
	v_cvt_pk_bf16_f32 v85, v86, v87
	v_cvt_pk_bf16_f32 v86, v80, v81
	s_waitcnt lgkmcnt(0)
	v_add_f32_e32 v80, v88, v89
	ds_bpermute_b32 v81, v217, v80
	v_cvt_pk_bf16_f32 v87, v82, v83
	v_lshl_add_u64 v[82:83], s[80:81], 0, v[100:101]
	global_store_dwordx4 v[82:83], v[84:87], off
	s_and_saveexec_b64 s[20:21], s[0:1]
	s_cbranch_execz .LBB0_1213
	v_lshl_add_u64 v[82:83], v[202:203], 2, s[12:13]
	s_waitcnt lgkmcnt(0)
	v_add_f32_e32 v80, v80, v81
	global_atomic_add_f32 v[82:83], v80, off
; __device__ __forceinline__ unsigned cvtpk(float lo, float hi) { f32x2_t v = {lo, hi}; bf16x2_t b = __builtin_convertvector(v, bf16x2_t); return __builtin_bit_cast(unsigned, b); }
;     __device__ __forceinline__ void operator()(const pg8::f32x4 (&acc)[2][2][4][2], const pg8::Unit& u, int wr, int wc, int fr, int fq) const {
;     ...
;         for (int ai = 0; ai < 2; ++ai) {
;             pg8::f32x4 rv[4][2][2];
; #pragma unroll
;             for (int m = 0; m < 4; ++m)
; #pragma unroll
;                 for (int bj = 0; bj < 2; ++bj) { const size_t off = (size_t)(row0 + ai * 128 + m * 16) * DM + colb + bj * 128;
;                     rv[m][bj][0] = *(const pg8::f32x4*)(R + off); rv[m][bj][1] = *(const pg8::f32x4*)(R + off + 4); }
; #pragma unroll
;             for (int m = 0; m < 4; ++m) {
;                 const int row = row0 + ai * 128 + m * 16;
;                 float sq = 0.f;
; #pragma unroll
;                 for (int bj = 0; bj < 2; ++bj) {
;                     const size_t off = (size_t)row * DM + colb + bj * 128;
;                     const pg8::f32x4 v0 = rv[m][bj][0] + acc[ai][bj][m][0] * alpha, v1 = rv[m][bj][1] + acc[ai][bj][m][1] * alpha;
;                     *(pg8::f32x4*)(X + off) = v0; *(pg8::f32x4*)(X + off + 4) = v1;
;                     u32x4 w; w[0] = cvtpk(v0[0], v0[1]); w[1] = cvtpk(v0[2], v0[3]); w[2] = cvtpk(v1[0], v1[1]); w[3] = cvtpk(v1[2], v1[3]);
;                     *(u32x4*)(XB + off) = w;
;                     sq += (v0[0] * v0[0] + v0[1] * v0[1]) + (v0[2] * v0[2] + v0[3] * v0[3]) + (v1[0] * v1[0] + v1[1] * v1[1]) + (v1[2] * v1[2] + v1[3] * v1[3]);
;                 }
;                 sq += __shfl_xor(sq, 16); sq += __shfl_xor(sq, 32);
;                 if (fq == 0) atomicAdd(ssout + row, sq);
;             }
.LBB0_1213:
	s_or_b64 exec, exec, s[20:21]
	s_waitcnt lgkmcnt(0)
	v_lshlrev_b64 v[80:81], 11, v[198:199]
	v_pk_fma_f32 v[78:79], v[78:79], 0.5, v[142:143] op_sel_hi:[1,0,1]
	v_pk_fma_f32 v[76:77], v[76:77], 0.5, v[140:141] op_sel_hi:[1,0,1]
	v_lshl_add_u64 v[84:85], v[80:81], 0, v[192:193]
	v_pk_fma_f32 v[74:75], v[74:75], 0.5, v[138:139] op_sel_hi:[1,0,1]
	v_pk_fma_f32 v[72:73], v[72:73], 0.5, v[136:137] op_sel_hi:[1,0,1]
	global_store_dwordx4 v[200:201], v[76:79], off nt
	global_store_dwordx4 v[200:201], v[72:75], off offset:16 nt
	v_cvt_pk_bf16_f32 v80, v76, v77
	v_mul_f32_e32 v77, v77, v77
	v_fmac_f32_e32 v77, v76, v76
	v_mul_f32_e32 v76, v79, v79
	v_cvt_pk_bf16_f32 v82, v72, v73
	v_fmac_f32_e32 v76, v78, v78
	v_mul_f32_e32 v73, v73, v73
	v_add_f32_e32 v76, v77, v76
	v_fmac_f32_e32 v73, v72, v72
	v_add_f32_e32 v72, v73, v76
	v_mul_f32_e32 v73, v75, v75
	v_fmac_f32_e32 v73, v74, v74
	v_pk_fma_f32 v[70:71], v[70:71], 0.5, v[134:135] op_sel_hi:[1,0,1]
	v_pk_fma_f32 v[68:69], v[68:69], 0.5, v[132:133] op_sel_hi:[1,0,1]
	v_cvt_pk_bf16_f32 v83, v74, v75
	v_add_f32_e32 v72, v73, v72
	v_mul_f32_e32 v73, v69, v69
	v_mul_f32_e32 v74, v71, v71
	v_pk_fma_f32 v[64:65], v[64:65], 0.5, v[128:129] op_sel_hi:[1,0,1]
	v_fmac_f32_e32 v73, v68, v68
	v_fmac_f32_e32 v74, v70, v70
	v_add_f32_e32 v73, v73, v74
	v_mul_f32_e32 v74, v65, v65
	v_pk_fma_f32 v[66:67], v[66:67], 0.5, v[130:131] op_sel_hi:[1,0,1]
	v_fmac_f32_e32 v74, v64, v64
	v_add_f32_e32 v73, v74, v73
	v_mul_f32_e32 v74, v67, v67
	v_fmac_f32_e32 v74, v66, v66
	v_add_f32_e32 v73, v74, v73
	v_add_f32_e32 v72, v72, v73
	ds_bpermute_b32 v73, v218, v72
	v_lshlrev_b64 v[84:85], 1, v[84:85]
	v_cvt_pk_bf16_f32 v81, v78, v79
	v_lshl_add_u64 v[86:87], s[80:81], 0, v[84:85]
	global_store_dwordx4 v[86:87], v[80:83], off
	global_store_dwordx4 v[200:201], v[68:71], off offset:512 nt
	global_store_dwordx4 v[200:201], v[64:67], off offset:528 nt
	v_or_b32_e32 v84, 0x100, v84
	v_cvt_pk_bf16_f32 v68, v68, v69
	v_cvt_pk_bf16_f32 v69, v70, v71
	v_cvt_pk_bf16_f32 v70, v64, v65
	s_waitcnt lgkmcnt(0)
	v_add_f32_e32 v64, v72, v73
	ds_bpermute_b32 v65, v217, v64
	v_cvt_pk_bf16_f32 v71, v66, v67
	v_lshl_add_u64 v[66:67], s[80:81], 0, v[84:85]
	global_store_dwordx4 v[66:67], v[68:71], off
	s_and_saveexec_b64 s[20:21], s[0:1]
	s_cbranch_execz .LBB0_1215
	v_lshl_add_u64 v[66:67], v[198:199], 2, s[12:13]
	s_waitcnt lgkmcnt(0)
	v_add_f32_e32 v64, v64, v65
	global_atomic_add_f32 v[66:67], v64, off
.LBB0_1215:
	s_or_b64 exec, exec, s[20:21]
	v_add_u32_e32 v124, 0x80, v194
	v_ashrrev_i32_e32 v125, 31, v124
	s_waitcnt lgkmcnt(0)
	v_lshlrev_b64 v[64:65], 13, v[124:125]
	v_lshl_add_u64 v[142:143], v[196:197], 0, v[64:65]
	global_load_dwordx4 v[126:129], v[142:143], off
	global_load_dwordx4 v[130:133], v[142:143], off offset:16
	global_load_dwordx4 v[134:137], v[142:143], off offset:512
	global_load_dwordx4 v[138:141], v[142:143], off offset:528
	v_add_u32_e32 v120, 0x90, v194
	v_add_u32_e32 v116, 0xa0, v194
	v_add_u32_e32 v112, 0xb0, v194
	v_ashrrev_i32_e32 v121, 31, v120
	v_ashrrev_i32_e32 v117, 31, v116
	v_ashrrev_i32_e32 v113, 31, v112
	v_lshlrev_b64 v[64:65], 13, v[120:121]
	v_lshlrev_b64 v[66:67], 13, v[116:117]
	v_lshlrev_b64 v[68:69], 13, v[112:113]
	v_lshl_add_u64 v[122:123], v[196:197], 0, v[64:65]
	v_lshl_add_u64 v[118:119], v[196:197], 0, v[66:67]
	v_lshl_add_u64 v[114:115], v[196:197], 0, v[68:69]
	global_load_dwordx4 v[104:107], v[122:123], off offset:16
	global_load_dwordx4 v[108:111], v[122:123], off
	global_load_dwordx4 v[96:99], v[122:123], off offset:528
	global_load_dwordx4 v[100:103], v[122:123], off offset:512
	global_load_dwordx4 v[88:91], v[118:119], off offset:16
	global_load_dwordx4 v[92:95], v[118:119], off
	global_load_dwordx4 v[80:83], v[118:119], off offset:528
	global_load_dwordx4 v[84:87], v[118:119], off offset:512
	global_load_dwordx4 v[72:75], v[114:115], off offset:16
	global_load_dwordx4 v[76:79], v[114:115], off
	global_load_dwordx4 v[64:67], v[114:115], off offset:528
	global_load_dwordx4 v[68:71], v[114:115], off offset:512
	v_lshlrev_b64 v[144:145], 11, v[124:125]
	v_lshl_add_u64 v[144:145], v[144:145], 0, v[192:193]
	v_lshlrev_b64 v[144:145], 1, v[144:145]
	v_lshl_add_u64 v[146:147], s[80:81], 0, v[144:145]
	v_or_b32_e32 v144, 0x100, v144
	s_waitcnt vmcnt(15)
	v_pk_fma_f32 v[62:63], v[62:63], 0.5, v[128:129] op_sel_hi:[1,0,1]
	v_pk_fma_f32 v[60:61], v[60:61], 0.5, v[126:127] op_sel_hi:[1,0,1]
	s_waitcnt vmcnt(13)
	v_pk_fma_f32 v[54:55], v[54:55], 0.5, v[136:137] op_sel_hi:[1,0,1]
	v_pk_fma_f32 v[52:53], v[52:53], 0.5, v[134:135] op_sel_hi:[1,0,1]
	v_pk_fma_f32 v[58:59], v[58:59], 0.5, v[132:133] op_sel_hi:[1,0,1]
	v_pk_fma_f32 v[56:57], v[56:57], 0.5, v[130:131] op_sel_hi:[1,0,1]
	s_waitcnt vmcnt(12)
	v_pk_fma_f32 v[48:49], v[48:49], 0.5, v[138:139] op_sel_hi:[1,0,1]
	global_store_dwordx4 v[142:143], v[60:63], off nt
	global_store_dwordx4 v[142:143], v[56:59], off offset:16 nt
	v_cvt_pk_bf16_f32 v126, v60, v61
	v_cvt_pk_bf16_f32 v127, v62, v63
	v_mul_f32_e32 v61, v61, v61
	v_mul_f32_e32 v63, v63, v63
	v_mul_f32_e32 v130, v53, v53
	v_mul_f32_e32 v131, v55, v55
	v_pk_fma_f32 v[50:51], v[50:51], 0.5, v[140:141] op_sel_hi:[1,0,1]
	v_cvt_pk_bf16_f32 v128, v56, v57
	v_cvt_pk_bf16_f32 v129, v58, v59
	v_mul_f32_e32 v57, v57, v57
	v_mul_f32_e32 v59, v59, v59
	v_mul_f32_e32 v132, v49, v49
	v_fmac_f32_e32 v61, v60, v60
	v_fmac_f32_e32 v63, v62, v62
	v_fmac_f32_e32 v130, v52, v52
	v_fmac_f32_e32 v131, v54, v54
	v_mul_f32_e32 v133, v51, v51
	v_fmac_f32_e32 v57, v56, v56
	v_fmac_f32_e32 v59, v58, v58
	v_fmac_f32_e32 v132, v48, v48
	v_add_f32_e32 v56, v61, v63
	v_add_f32_e32 v58, v130, v131
	v_fmac_f32_e32 v133, v50, v50
	v_add_f32_e32 v56, v57, v56
	v_add_f32_e32 v57, v132, v58
	v_add_f32_e32 v56, v59, v56
	v_add_f32_e32 v57, v133, v57
	v_add_f32_e32 v56, v56, v57
	ds_bpermute_b32 v57, v218, v56
	global_store_dwordx4 v[146:147], v[126:129], off
	global_store_dwordx4 v[142:143], v[52:55], off offset:512 nt
	global_store_dwordx4 v[142:143], v[48:51], off offset:528 nt
	s_nop 0
	v_cvt_pk_bf16_f32 v52, v52, v53
	v_cvt_pk_bf16_f32 v53, v54, v55
	v_cvt_pk_bf16_f32 v54, v48, v49
	s_waitcnt lgkmcnt(0)
	v_add_f32_e32 v48, v56, v57
	ds_bpermute_b32 v49, v217, v48
	v_cvt_pk_bf16_f32 v55, v50, v51
	v_lshl_add_u64 v[50:51], s[80:81], 0, v[144:145]
	global_store_dwordx4 v[50:51], v[52:55], off
	s_and_saveexec_b64 s[20:21], s[0:1]
	s_cbranch_execz .LBB0_1217
	v_lshl_add_u64 v[50:51], v[124:125], 2, s[12:13]
	s_waitcnt lgkmcnt(0)
	v_add_f32_e32 v48, v48, v49
	global_atomic_add_f32 v[50:51], v48, off
; __device__ __forceinline__ unsigned cvtpk(float lo, float hi) { f32x2_t v = {lo, hi}; bf16x2_t b = __builtin_convertvector(v, bf16x2_t); return __builtin_bit_cast(unsigned, b); }
;     __device__ __forceinline__ void operator()(const pg8::f32x4 (&acc)[2][2][4][2], const pg8::Unit& u, int wr, int wc, int fr, int fq) const {
;     ...
;             for (int m = 0; m < 4; ++m) {
;                 const int row = row0 + ai * 128 + m * 16;
;                 float sq = 0.f;
; #pragma unroll
;                 for (int bj = 0; bj < 2; ++bj) {
;                     const size_t off = (size_t)row * DM + colb + bj * 128;
;                     const pg8::f32x4 v0 = rv[m][bj][0] + acc[ai][bj][m][0] * alpha, v1 = rv[m][bj][1] + acc[ai][bj][m][1] * alpha;
;                     *(pg8::f32x4*)(X + off) = v0; *(pg8::f32x4*)(X + off + 4) = v1;
;                     u32x4 w; w[0] = cvtpk(v0[0], v0[1]); w[1] = cvtpk(v0[2], v0[3]); w[2] = cvtpk(v1[0], v1[1]); w[3] = cvtpk(v1[2], v1[3]);
;                     *(u32x4*)(XB + off) = w;
;                     sq += (v0[0] * v0[0] + v0[1] * v0[1]) + (v0[2] * v0[2] + v0[3] * v0[3]) + (v1[0] * v1[0] + v1[1] * v1[1]) + (v1[2] * v1[2] + v1[3] * v1[3]);
;                 }
;                 sq += __shfl_xor(sq, 16); sq += __shfl_xor(sq, 32);
;                 if (fq == 0) atomicAdd(ssout + row, sq);
;             }
.LBB0_1217:
	s_or_b64 exec, exec, s[20:21]
	s_waitcnt lgkmcnt(0)
	v_lshlrev_b64 v[48:49], 11, v[120:121]
	s_waitcnt vmcnt(16)
	v_pk_fma_f32 v[46:47], v[46:47], 0.5, v[110:111] op_sel_hi:[1,0,1]
	v_pk_fma_f32 v[44:45], v[44:45], 0.5, v[108:109] op_sel_hi:[1,0,1]
	v_lshl_add_u64 v[52:53], v[48:49], 0, v[192:193]
	v_pk_fma_f32 v[42:43], v[42:43], 0.5, v[106:107] op_sel_hi:[1,0,1]
	v_pk_fma_f32 v[40:41], v[40:41], 0.5, v[104:105] op_sel_hi:[1,0,1]
	global_store_dwordx4 v[122:123], v[44:47], off nt
	global_store_dwordx4 v[122:123], v[40:43], off offset:16 nt
	v_cvt_pk_bf16_f32 v48, v44, v45
	v_mul_f32_e32 v45, v45, v45
	v_fmac_f32_e32 v45, v44, v44
	v_mul_f32_e32 v44, v47, v47
	v_cvt_pk_bf16_f32 v50, v40, v41
	v_fmac_f32_e32 v44, v46, v46
	v_mul_f32_e32 v41, v41, v41
	v_add_f32_e32 v44, v45, v44
	v_fmac_f32_e32 v41, v40, v40
	v_add_f32_e32 v40, v41, v44
	v_mul_f32_e32 v41, v43, v43
	v_fmac_f32_e32 v41, v42, v42
	s_waitcnt vmcnt(16)
	v_pk_fma_f32 v[38:39], v[38:39], 0.5, v[102:103] op_sel_hi:[1,0,1]
	v_pk_fma_f32 v[36:37], v[36:37], 0.5, v[100:101] op_sel_hi:[1,0,1]
	v_cvt_pk_bf16_f32 v51, v42, v43
	v_add_f32_e32 v40, v41, v40
	v_mul_f32_e32 v41, v37, v37
	v_mul_f32_e32 v42, v39, v39
	v_pk_fma_f32 v[32:33], v[32:33], 0.5, v[96:97] op_sel_hi:[1,0,1]
	v_fmac_f32_e32 v41, v36, v36
	v_fmac_f32_e32 v42, v38, v38
	v_add_f32_e32 v41, v41, v42
	v_mul_f32_e32 v42, v33, v33
	v_pk_fma_f32 v[34:35], v[34:35], 0.5, v[98:99] op_sel_hi:[1,0,1]
	v_fmac_f32_e32 v42, v32, v32
	v_add_f32_e32 v41, v42, v41
	v_mul_f32_e32 v42, v35, v35
	v_fmac_f32_e32 v42, v34, v34
	v_add_f32_e32 v41, v42, v41
	v_add_f32_e32 v40, v40, v41
	ds_bpermute_b32 v41, v218, v40
	v_lshlrev_b64 v[52:53], 1, v[52:53]
	v_cvt_pk_bf16_f32 v49, v46, v47
	v_lshl_add_u64 v[54:55], s[80:81], 0, v[52:53]
	global_store_dwordx4 v[54:55], v[48:51], off
	global_store_dwordx4 v[122:123], v[36:39], off offset:512 nt
	global_store_dwordx4 v[122:123], v[32:35], off offset:528 nt
	v_or_b32_e32 v52, 0x100, v52
	v_cvt_pk_bf16_f32 v36, v36, v37
	v_cvt_pk_bf16_f32 v37, v38, v39
	v_cvt_pk_bf16_f32 v38, v32, v33
	s_waitcnt lgkmcnt(0)
	v_add_f32_e32 v32, v40, v41
	ds_bpermute_b32 v33, v217, v32
	v_cvt_pk_bf16_f32 v39, v34, v35
	v_lshl_add_u64 v[34:35], s[80:81], 0, v[52:53]
	global_store_dwordx4 v[34:35], v[36:39], off
	s_and_saveexec_b64 s[20:21], s[0:1]
	s_cbranch_execz .LBB0_1219
	v_lshl_add_u64 v[34:35], v[120:121], 2, s[12:13]
	s_waitcnt lgkmcnt(0)
	v_add_f32_e32 v32, v32, v33
	global_atomic_add_f32 v[34:35], v32, off
; __device__ __forceinline__ unsigned cvtpk(float lo, float hi) { f32x2_t v = {lo, hi}; bf16x2_t b = __builtin_convertvector(v, bf16x2_t); return __builtin_bit_cast(unsigned, b); }
;     __device__ __forceinline__ void operator()(const pg8::f32x4 (&acc)[2][2][4][2], const pg8::Unit& u, int wr, int wc, int fr, int fq) const {
;     ...
;             for (int m = 0; m < 4; ++m) {
;                 const int row = row0 + ai * 128 + m * 16;
;                 float sq = 0.f;
; #pragma unroll
;                 for (int bj = 0; bj < 2; ++bj) {
;                     const size_t off = (size_t)row * DM + colb + bj * 128;
;                     const pg8::f32x4 v0 = rv[m][bj][0] + acc[ai][bj][m][0] * alpha, v1 = rv[m][bj][1] + acc[ai][bj][m][1] * alpha;
;                     *(pg8::f32x4*)(X + off) = v0; *(pg8::f32x4*)(X + off + 4) = v1;
;                     u32x4 w; w[0] = cvtpk(v0[0], v0[1]); w[1] = cvtpk(v0[2], v0[3]); w[2] = cvtpk(v1[0], v1[1]); w[3] = cvtpk(v1[2], v1[3]);
;                     *(u32x4*)(XB + off) = w;
;                     sq += (v0[0] * v0[0] + v0[1] * v0[1]) + (v0[2] * v0[2] + v0[3] * v0[3]) + (v1[0] * v1[0] + v1[1] * v1[1]) + (v1[2] * v1[2] + v1[3] * v1[3]);
;                 }
;                 sq += __shfl_xor(sq, 16); sq += __shfl_xor(sq, 32);
;                 if (fq == 0) atomicAdd(ssout + row, sq);
;             }
.LBB0_1219:
	s_or_b64 exec, exec, s[20:21]
	s_waitcnt lgkmcnt(0)
	v_lshlrev_b64 v[32:33], 11, v[116:117]
	s_waitcnt vmcnt(18)
	v_pk_fma_f32 v[30:31], v[30:31], 0.5, v[94:95] op_sel_hi:[1,0,1]
	v_pk_fma_f32 v[28:29], v[28:29], 0.5, v[92:93] op_sel_hi:[1,0,1]
	v_lshl_add_u64 v[36:37], v[32:33], 0, v[192:193]
	v_pk_fma_f32 v[26:27], v[26:27], 0.5, v[90:91] op_sel_hi:[1,0,1]
	v_pk_fma_f32 v[24:25], v[24:25], 0.5, v[88:89] op_sel_hi:[1,0,1]
	global_store_dwordx4 v[118:119], v[28:31], off nt
	global_store_dwordx4 v[118:119], v[24:27], off offset:16 nt
	v_cvt_pk_bf16_f32 v32, v28, v29
	v_mul_f32_e32 v29, v29, v29
	v_fmac_f32_e32 v29, v28, v28
	v_mul_f32_e32 v28, v31, v31
	v_cvt_pk_bf16_f32 v34, v24, v25
	v_fmac_f32_e32 v28, v30, v30
	v_mul_f32_e32 v25, v25, v25
	v_add_f32_e32 v28, v29, v28
	v_fmac_f32_e32 v25, v24, v24
	v_add_f32_e32 v24, v25, v28
	v_mul_f32_e32 v25, v27, v27
	v_fmac_f32_e32 v25, v26, v26
	s_waitcnt vmcnt(18)
	v_pk_fma_f32 v[22:23], v[22:23], 0.5, v[86:87] op_sel_hi:[1,0,1]
	v_pk_fma_f32 v[20:21], v[20:21], 0.5, v[84:85] op_sel_hi:[1,0,1]
	v_cvt_pk_bf16_f32 v35, v26, v27
	v_add_f32_e32 v24, v25, v24
	v_mul_f32_e32 v25, v21, v21
	v_mul_f32_e32 v26, v23, v23
	v_pk_fma_f32 v[16:17], v[16:17], 0.5, v[80:81] op_sel_hi:[1,0,1]
	v_fmac_f32_e32 v25, v20, v20
	v_fmac_f32_e32 v26, v22, v22
	v_add_f32_e32 v25, v25, v26
	v_mul_f32_e32 v26, v17, v17
	v_pk_fma_f32 v[18:19], v[18:19], 0.5, v[82:83] op_sel_hi:[1,0,1]
	v_fmac_f32_e32 v26, v16, v16
	v_add_f32_e32 v25, v26, v25
	v_mul_f32_e32 v26, v19, v19
	v_fmac_f32_e32 v26, v18, v18
	v_add_f32_e32 v25, v26, v25
	v_add_f32_e32 v24, v24, v25
	ds_bpermute_b32 v25, v218, v24
	v_lshlrev_b64 v[36:37], 1, v[36:37]
	v_cvt_pk_bf16_f32 v33, v30, v31
	v_lshl_add_u64 v[38:39], s[80:81], 0, v[36:37]
	global_store_dwordx4 v[38:39], v[32:35], off
	global_store_dwordx4 v[118:119], v[20:23], off offset:512 nt
	global_store_dwordx4 v[118:119], v[16:19], off offset:528 nt
	v_or_b32_e32 v36, 0x100, v36
	v_cvt_pk_bf16_f32 v20, v20, v21
	v_cvt_pk_bf16_f32 v21, v22, v23
	v_cvt_pk_bf16_f32 v22, v16, v17
	s_waitcnt lgkmcnt(0)
	v_add_f32_e32 v16, v24, v25
	ds_bpermute_b32 v17, v217, v16
	v_cvt_pk_bf16_f32 v23, v18, v19
	v_lshl_add_u64 v[18:19], s[80:81], 0, v[36:37]
	global_store_dwordx4 v[18:19], v[20:23], off
	s_and_saveexec_b64 s[20:21], s[0:1]
	s_cbranch_execz .LBB0_1221
	v_lshl_add_u64 v[18:19], v[116:117], 2, s[12:13]
	s_waitcnt lgkmcnt(0)
	v_add_f32_e32 v16, v16, v17
	global_atomic_add_f32 v[18:19], v16, off
.LBB0_1221:
	s_or_b64 exec, exec, s[20:21]
	s_waitcnt lgkmcnt(0)
	v_lshlrev_b64 v[16:17], 11, v[112:113]
	s_waitcnt vmcnt(20)
	v_pk_fma_f32 v[14:15], v[14:15], 0.5, v[78:79] op_sel_hi:[1,0,1]
	v_pk_fma_f32 v[12:13], v[12:13], 0.5, v[76:77] op_sel_hi:[1,0,1]
	v_lshl_add_u64 v[20:21], v[16:17], 0, v[192:193]
	v_pk_fma_f32 v[10:11], v[10:11], 0.5, v[74:75] op_sel_hi:[1,0,1]
	v_pk_fma_f32 v[8:9], v[8:9], 0.5, v[72:73] op_sel_hi:[1,0,1]
	global_store_dwordx4 v[114:115], v[12:15], off nt
	global_store_dwordx4 v[114:115], v[8:11], off offset:16 nt
	v_cvt_pk_bf16_f32 v16, v12, v13
	v_mul_f32_e32 v13, v13, v13
	v_fmac_f32_e32 v13, v12, v12
	v_mul_f32_e32 v12, v15, v15
	v_cvt_pk_bf16_f32 v18, v8, v9
	v_fmac_f32_e32 v12, v14, v14
	v_mul_f32_e32 v9, v9, v9
	v_add_f32_e32 v12, v13, v12
	v_fmac_f32_e32 v9, v8, v8
	v_add_f32_e32 v8, v9, v12
	v_mul_f32_e32 v9, v11, v11
	v_fmac_f32_e32 v9, v10, v10
	s_waitcnt vmcnt(20)
	v_pk_fma_f32 v[6:7], v[6:7], 0.5, v[70:71] op_sel_hi:[1,0,1]
	v_pk_fma_f32 v[4:5], v[4:5], 0.5, v[68:69] op_sel_hi:[1,0,1]
	v_cvt_pk_bf16_f32 v19, v10, v11
	v_add_f32_e32 v8, v9, v8
	v_mul_f32_e32 v9, v5, v5
	v_mul_f32_e32 v10, v7, v7
	v_pk_fma_f32 v[0:1], v[0:1], 0.5, v[64:65] op_sel_hi:[1,0,1]
	v_fmac_f32_e32 v9, v4, v4
	v_fmac_f32_e32 v10, v6, v6
	v_add_f32_e32 v9, v9, v10
	v_mul_f32_e32 v10, v1, v1
	v_pk_fma_f32 v[2:3], v[2:3], 0.5, v[66:67] op_sel_hi:[1,0,1]
	v_fmac_f32_e32 v10, v0, v0
	v_add_f32_e32 v9, v10, v9
	v_mul_f32_e32 v10, v3, v3
	v_fmac_f32_e32 v10, v2, v2
	v_add_f32_e32 v9, v10, v9
	v_add_f32_e32 v8, v8, v9
	ds_bpermute_b32 v9, v218, v8
	v_lshlrev_b64 v[20:21], 1, v[20:21]
	v_cvt_pk_bf16_f32 v17, v14, v15
	v_lshl_add_u64 v[22:23], s[80:81], 0, v[20:21]
	global_store_dwordx4 v[22:23], v[16:19], off
	global_store_dwordx4 v[114:115], v[4:7], off offset:512 nt
	global_store_dwordx4 v[114:115], v[0:3], off offset:528 nt
	v_or_b32_e32 v20, 0x100, v20
	v_cvt_pk_bf16_f32 v4, v4, v5
	v_cvt_pk_bf16_f32 v5, v6, v7
	v_cvt_pk_bf16_f32 v6, v0, v1
	s_waitcnt lgkmcnt(0)
	v_add_f32_e32 v0, v8, v9
	ds_bpermute_b32 v1, v217, v0
	v_cvt_pk_bf16_f32 v7, v2, v3
	v_lshl_add_u64 v[2:3], s[80:81], 0, v[20:21]
	global_store_dwordx4 v[2:3], v[4:7], off
	s_and_saveexec_b64 s[20:21], s[0:1]
	s_cbranch_execz .LBB0_1223
	v_lshl_add_u64 v[2:3], v[112:113], 2, s[12:13]
	s_waitcnt lgkmcnt(0)
	v_add_f32_e32 v0, v0, v1
	global_atomic_add_f32 v[2:3], v0, off
